# GEMM K-loop control SALU moved ahead of the loop-back barrier (loop-edge edit) in the dqkv, up, N1024 and tail loops
# baseline (speedup 1.0000x reference)
; #define PG8_STAGE(bufoff, gbase, voff) do { _Pragma("unroll") for (int _i = 0; _i < 2; ++_i) \
;         __builtin_amdgcn_global_load_lds((const unsigned*)((const char*)(gbase) + (size_t)_i * r64##voff + voff), (PG8_LAS unsigned*)(lds + (bufoff) + ldsw + _i * 8192), 16, 0, 0); } while (0)
; #define PG8_LDA(dst, b, h) do { _Pragma("unroll") for (int m = 0; m < 4; ++m) _Pragma("unroll") for (int k = 0; k < 2; ++k) dst[m][k] = *(const PG8_LAS bf16x8*)(lds + PG8_SA(b, h) + aoff + m * 2048 + k * 1024); } while (0)
; #define PG8_LDB(dst, b, h) do { _Pragma("unroll") for (int n = 0; n < 2; ++n) _Pragma("unroll") for (int k = 0; k < 2; ++k) dst[n][k] = *(const PG8_LAS bf16x8*)(lds + PG8_SB(b, h) + boff + n * 2048 + k * 1024); } while (0)
; #define PG8_MMA(ai, bj, At, Bt) do { __builtin_amdgcn_s_setprio(1); _Pragma("unroll") for (int m = 0; m < 4; ++m) _Pragma("unroll") for (int n = 0; n < 2; ++n) _Pragma("unroll") for (int k = 0; k < 2; ++k) \
;         acc[ai][bj][m][n] = __builtin_amdgcn_mfma_f32_16x16x32_bf16(Bt[n][k], At[m][k], acc[ai][bj][m][n], 0, 0, 0); __builtin_amdgcn_s_setprio(0); } while (0)
; #define PG8_WAIT_V(n) asm volatile("s_waitcnt vmcnt(" #n ")" ::: "memory")
; #define PG8_WAIT_L(n) asm volatile("s_waitcnt lgkmcnt(" #n ")" ::: "memory")
; template <class Epi, class Sched, bool ALIGN_EPI = false, bool SP2 = false>
; __device__ __forceinline__ void gemm_phase(PG8_LAS unsigned char* lds, const Gemm g, const Sched& S, const Epi& E, int wid0) {
;     ...
;             const bool last = (t == nt - 2);
;             const char* a1 = cA + (size_t)(t + 1) * kstep;
;             const char* a2 = last ? nA : cA + (size_t)(t + 2) * kstep; const char* b2 = last ? nB : cB + (size_t)(t + 2) * kstep;
;             const char* a3 = a2 + kstep; const char* b3 = b2 + kstep;
;             if (last && has_next) S.a_ready(nxt);
;             if constexpr (SP2) {
;             PG8_LDB(B0, 0, 0); PG8_LDB(B1, 0, 1); PG8_SCHED; PG8_LDA(At, 0, 0); PG8_STAGE(PG8_SA(1, 1), a1 + hstepA, voffA);
;             PG8_WAIT_V(8); PG8_WAIT_L(0); PG8_BAR; PG8_MMA(0, 0, At, B0); PG8_MMA(0, 1, At, B1); PG8_BAR; PG8_SCHED;
;             PG8_LDA(At, 0, 1); PG8_STAGE(PG8_SB(0, 0), b2, voffB); PG8_STAGE(PG8_SB(0, 1), b2 + hstepB, voffB); PG8_STAGE(PG8_SA(0, 0), a2, voffA);
;             PG8_WAIT_V(8); PG8_WAIT_L(0); PG8_BAR; PG8_MMA(1, 0, At, B0); PG8_MMA(1, 1, At, B1); PG8_BAR; PG8_SCHED;
.LBB0_205:
	s_add_u32 s28, s26, 0xfffc0080
	s_addc_u32 s29, s27, -1
	s_add_i32 s86, 0, 0x10000
	s_cmp_eq_u32 s79, 12
	s_cselect_b32 s29, s19, s29
	s_cselect_b32 s28, s25, s28
	v_add_u32_e32 v144, s86, v1
	s_cselect_b32 s85, s17, s78
	s_cselect_b32 s84, s30, s31
	s_add_i32 s88, 0, 0x14000
	ds_read_b128 v[136:139], v144
	ds_read_b128 v[140:143], v144 offset:1024
	ds_read_b128 v[148:151], v144 offset:2048
	ds_read_b128 v[152:155], v144 offset:3072
	v_add_u32_e32 v144, s88, v1
	ds_read_b128 v[156:159], v144
	ds_read_b128 v[160:163], v144 offset:1024
	ds_read_b128 v[164:167], v144 offset:2048
	ds_read_b128 v[168:171], v144 offset:3072
	v_lshl_add_u64 v[144:145], s[26:27], 0, v[134:135]
	s_add_i32 m0, s5, 0xc000
	ds_read_b128 v[172:175], v146
	ds_read_b128 v[176:179], v146 offset:1024
	ds_read_b128 v[180:183], v146 offset:2048
	ds_read_b128 v[184:187], v146 offset:3072
	ds_read_b128 v[188:191], v146 offset:4096
	ds_read_b128 v[192:195], v146 offset:5120
	ds_read_b128 v[196:199], v146 offset:6144
	ds_read_b128 v[200:203], v146 offset:7168
	global_load_lds_dwordx4 v[144:145], off
	v_lshl_add_u64 v[144:145], v[144:145], 0, s[64:65]
	s_add_i32 m0, s5, 0xe000
	s_nop 0
	global_load_lds_dwordx4 v[144:145], off
	s_waitcnt vmcnt(8)
	s_waitcnt lgkmcnt(0)
	s_barrier
	s_setprio 1
	s_waitcnt lgkmcnt(0)
	v_mfma_f32_16x16x32_bf16 v[126:129], v[136:139], v[172:175], v[126:129]
	v_mfma_f32_16x16x32_bf16 v[122:125], v[148:151], v[172:175], v[122:125]
	v_mfma_f32_16x16x32_bf16 v[110:113], v[136:139], v[180:183], v[110:113]
	v_mfma_f32_16x16x32_bf16 v[106:109], v[148:151], v[180:183], v[106:109]
	v_mfma_f32_16x16x32_bf16 v[94:97], v[136:139], v[188:191], v[94:97]
	v_mfma_f32_16x16x32_bf16 v[90:93], v[148:151], v[188:191], v[90:93]
	v_mfma_f32_16x16x32_bf16 v[78:81], v[136:139], v[196:199], v[78:81]
	v_mfma_f32_16x16x32_bf16 v[74:77], v[148:151], v[196:199], v[74:77]
	v_mfma_f32_16x16x32_bf16 v[126:129], v[140:143], v[176:179], v[126:129]
	v_mfma_f32_16x16x32_bf16 v[122:125], v[152:155], v[176:179], v[122:125]
	v_mfma_f32_16x16x32_bf16 v[110:113], v[140:143], v[184:187], v[110:113]
	v_mfma_f32_16x16x32_bf16 v[106:109], v[152:155], v[184:187], v[106:109]
	v_mfma_f32_16x16x32_bf16 v[94:97], v[140:143], v[192:195], v[94:97]
	v_mfma_f32_16x16x32_bf16 v[90:93], v[152:155], v[192:195], v[90:93]
	v_mfma_f32_16x16x32_bf16 v[78:81], v[140:143], v[200:203], v[78:81]
	v_mfma_f32_16x16x32_bf16 v[74:77], v[152:155], v[200:203], v[74:77]
	s_setprio 0
	s_setprio 1
	v_mfma_f32_16x16x32_bf16 v[118:121], v[156:159], v[172:175], v[118:121]
	v_mfma_f32_16x16x32_bf16 v[114:117], v[164:167], v[172:175], v[114:117]
	v_mfma_f32_16x16x32_bf16 v[102:105], v[156:159], v[180:183], v[102:105]
	v_mfma_f32_16x16x32_bf16 v[98:101], v[164:167], v[180:183], v[98:101]
	v_mfma_f32_16x16x32_bf16 v[86:89], v[156:159], v[188:191], v[86:89]
	v_mfma_f32_16x16x32_bf16 v[82:85], v[164:167], v[188:191], v[82:85]
	v_mfma_f32_16x16x32_bf16 v[70:73], v[156:159], v[196:199], v[70:73]
	v_mfma_f32_16x16x32_bf16 v[66:69], v[164:167], v[196:199], v[66:69]
	v_mfma_f32_16x16x32_bf16 v[118:121], v[160:163], v[176:179], v[118:121]
	v_mfma_f32_16x16x32_bf16 v[114:117], v[168:171], v[176:179], v[114:117]
	v_mfma_f32_16x16x32_bf16 v[102:105], v[160:163], v[184:187], v[102:105]
	v_mfma_f32_16x16x32_bf16 v[98:101], v[168:171], v[184:187], v[98:101]
	v_mfma_f32_16x16x32_bf16 v[86:89], v[160:163], v[192:195], v[86:89]
	v_mfma_f32_16x16x32_bf16 v[82:85], v[168:171], v[192:195], v[82:85]
	v_mfma_f32_16x16x32_bf16 v[70:73], v[160:163], v[200:203], v[70:73]
	v_mfma_f32_16x16x32_bf16 v[66:69], v[168:171], v[200:203], v[66:69]
	s_setprio 0
	s_barrier
	v_lshl_add_u64 v[144:145], s[84:85], 0, v[132:133]
	s_add_i32 s84, s86, s40
	s_mov_b32 m0, s84
	ds_read_b128 v[172:175], v146 offset:16384
	ds_read_b128 v[176:179], v146 offset:17408
	ds_read_b128 v[180:183], v146 offset:18432
	ds_read_b128 v[184:187], v146 offset:19456
	ds_read_b128 v[188:191], v146 offset:20480
	ds_read_b128 v[192:195], v146 offset:21504
	ds_read_b128 v[196:199], v146 offset:22528
	ds_read_b128 v[200:203], v146 offset:23552
	global_load_lds_dwordx4 v[144:145], off
	v_lshl_add_u64 v[204:205], v[144:145], 0, s[64:65]
	s_add_i32 m0, s84, 0x2000
	s_add_i32 s84, s88, s40
	global_load_lds_dwordx4 v[204:205], off
	v_lshl_add_u64 v[204:205], v[144:145], 0, s[66:67]
	s_mov_b32 m0, s84
	s_nop 0
	global_load_lds_dwordx4 v[204:205], off
	v_lshl_add_u64 v[204:205], v[144:145], 0, s[68:69]
	s_add_i32 m0, s84, 0x2000
	s_nop 0
	global_load_lds_dwordx4 v[204:205], off
	v_lshl_add_u64 v[204:205], s[28:29], 0, v[130:131]
	s_mov_b32 m0, s5
	v_lshl_add_u64 v[206:207], v[204:205], 0, s[64:65]
	global_load_lds_dwordx4 v[204:205], off
	s_mov_b32 m0, s41
	s_nop 0
	global_load_lds_dwordx4 v[206:207], off
	s_waitcnt vmcnt(8)
	s_waitcnt lgkmcnt(0)
	s_barrier
; #define PG8_STAGE(bufoff, gbase, voff) do { _Pragma("unroll") for (int _i = 0; _i < 2; ++_i) \
;         __builtin_amdgcn_global_load_lds((const unsigned*)((const char*)(gbase) + (size_t)_i * r64##voff + voff), (PG8_LAS unsigned*)(lds + (bufoff) + ldsw + _i * 8192), 16, 0, 0); } while (0)
; #define PG8_LDA(dst, b, h) do { _Pragma("unroll") for (int m = 0; m < 4; ++m) _Pragma("unroll") for (int k = 0; k < 2; ++k) dst[m][k] = *(const PG8_LAS bf16x8*)(lds + PG8_SA(b, h) + aoff + m * 2048 + k * 1024); } while (0)
; #define PG8_LDB(dst, b, h) do { _Pragma("unroll") for (int n = 0; n < 2; ++n) _Pragma("unroll") for (int k = 0; k < 2; ++k) dst[n][k] = *(const PG8_LAS bf16x8*)(lds + PG8_SB(b, h) + boff + n * 2048 + k * 1024); } while (0)
; #define PG8_MMA(ai, bj, At, Bt) do { __builtin_amdgcn_s_setprio(1); _Pragma("unroll") for (int m = 0; m < 4; ++m) _Pragma("unroll") for (int n = 0; n < 2; ++n) _Pragma("unroll") for (int k = 0; k < 2; ++k) \
;         acc[ai][bj][m][n] = __builtin_amdgcn_mfma_f32_16x16x32_bf16(Bt[n][k], At[m][k], acc[ai][bj][m][n], 0, 0, 0); __builtin_amdgcn_s_setprio(0); } while (0)
; #define PG8_WAIT_V(n) asm volatile("s_waitcnt vmcnt(" #n ")" ::: "memory")
; #define PG8_WAIT_L(n) asm volatile("s_waitcnt lgkmcnt(" #n ")" ::: "memory")
; #define PG8_BAR __builtin_amdgcn_s_barrier()
; #define PG8_SCHED __builtin_amdgcn_sched_barrier(0)
; template <class Epi, class Sched, bool ALIGN_EPI = false, bool SP2 = false>
; __device__ __forceinline__ void gemm_phase(PG8_LAS unsigned char* lds, const Gemm g, const Sched& S, const Epi& E, int wid0) {
;     ...
;             PG8_WAIT_V(8); PG8_WAIT_L(0); PG8_BAR; PG8_MMA(1, 0, At, B0); PG8_MMA(1, 1, At, B1); PG8_BAR; PG8_SCHED;
;             PG8_LDB(B0, 1, 0); PG8_LDB(B1, 1, 1); PG8_SCHED; PG8_LDA(At, 1, 0); PG8_STAGE(PG8_SA(0, 1), a2 + hstepA, voffA);
;             PG8_WAIT_V(8); PG8_WAIT_L(0); PG8_BAR; PG8_MMA(0, 0, At, B0); PG8_MMA(0, 1, At, B1); PG8_BAR; PG8_SCHED;
	s_setprio 1
	s_waitcnt lgkmcnt(0)
	v_mfma_f32_16x16x32_bf16 v[62:65], v[136:139], v[172:175], v[62:65]
	v_mfma_f32_16x16x32_bf16 v[58:61], v[148:151], v[172:175], v[58:61]
	v_mfma_f32_16x16x32_bf16 v[46:49], v[136:139], v[180:183], v[46:49]
	v_mfma_f32_16x16x32_bf16 v[42:45], v[148:151], v[180:183], v[42:45]
	v_mfma_f32_16x16x32_bf16 v[30:33], v[136:139], v[188:191], v[30:33]
	v_mfma_f32_16x16x32_bf16 v[26:29], v[148:151], v[188:191], v[26:29]
	v_mfma_f32_16x16x32_bf16 v[14:17], v[136:139], v[196:199], v[14:17]
	v_mfma_f32_16x16x32_bf16 v[10:13], v[148:151], v[196:199], v[10:13]
	v_mfma_f32_16x16x32_bf16 v[62:65], v[140:143], v[176:179], v[62:65]
	v_mfma_f32_16x16x32_bf16 v[58:61], v[152:155], v[176:179], v[58:61]
	v_mfma_f32_16x16x32_bf16 v[46:49], v[140:143], v[184:187], v[46:49]
	v_mfma_f32_16x16x32_bf16 v[42:45], v[152:155], v[184:187], v[42:45]
	v_mfma_f32_16x16x32_bf16 v[30:33], v[140:143], v[192:195], v[30:33]
	v_mfma_f32_16x16x32_bf16 v[26:29], v[152:155], v[192:195], v[26:29]
	v_mfma_f32_16x16x32_bf16 v[14:17], v[140:143], v[200:203], v[14:17]
	v_mfma_f32_16x16x32_bf16 v[10:13], v[152:155], v[200:203], v[10:13]
	s_setprio 0
	s_setprio 1
	v_mfma_f32_16x16x32_bf16 v[54:57], v[156:159], v[172:175], v[54:57]
	v_mfma_f32_16x16x32_bf16 v[50:53], v[164:167], v[172:175], v[50:53]
	v_mfma_f32_16x16x32_bf16 v[38:41], v[156:159], v[180:183], v[38:41]
	v_mfma_f32_16x16x32_bf16 v[34:37], v[164:167], v[180:183], v[34:37]
	v_mfma_f32_16x16x32_bf16 v[22:25], v[156:159], v[188:191], v[22:25]
	v_mfma_f32_16x16x32_bf16 v[18:21], v[164:167], v[188:191], v[18:21]
	v_mfma_f32_16x16x32_bf16 v[6:9], v[156:159], v[196:199], v[6:9]
	v_mfma_f32_16x16x32_bf16 v[2:5], v[164:167], v[196:199], v[2:5]
	v_mfma_f32_16x16x32_bf16 v[54:57], v[160:163], v[176:179], v[54:57]
	v_mfma_f32_16x16x32_bf16 v[50:53], v[168:171], v[176:179], v[50:53]
	v_mfma_f32_16x16x32_bf16 v[38:41], v[160:163], v[184:187], v[38:41]
	v_mfma_f32_16x16x32_bf16 v[34:37], v[168:171], v[184:187], v[34:37]
	v_mfma_f32_16x16x32_bf16 v[22:25], v[160:163], v[192:195], v[22:25]
	v_mfma_f32_16x16x32_bf16 v[18:21], v[168:171], v[192:195], v[18:21]
	v_mfma_f32_16x16x32_bf16 v[6:9], v[160:163], v[200:203], v[6:9]
	v_mfma_f32_16x16x32_bf16 v[2:5], v[168:171], v[200:203], v[2:5]
	s_setprio 0
	s_barrier
	s_add_i32 s28, 0, 0x18000
	v_add_u32_e32 v147, s28, v1
	s_add_i32 s29, 0, 0x1c000
	ds_read_b128 v[136:139], v147
	ds_read_b128 v[140:143], v147 offset:1024
	ds_read_b128 v[148:151], v147 offset:2048
	ds_read_b128 v[152:155], v147 offset:3072
	v_add_u32_e32 v147, s29, v1
	ds_read_b128 v[156:159], v147
	ds_read_b128 v[160:163], v147 offset:1024
	ds_read_b128 v[164:167], v147 offset:2048
	ds_read_b128 v[168:171], v147 offset:3072
	s_mov_b32 m0, s43
	v_lshl_add_u64 v[206:207], v[204:205], 0, s[66:67]
	ds_read_b128 v[172:175], v146 offset:32768
	ds_read_b128 v[176:179], v146 offset:33792
	ds_read_b128 v[180:183], v146 offset:34816
	ds_read_b128 v[184:187], v146 offset:35840
	ds_read_b128 v[188:191], v146 offset:36864
	ds_read_b128 v[192:195], v146 offset:37888
	ds_read_b128 v[196:199], v146 offset:38912
	ds_read_b128 v[200:203], v146 offset:39936
	global_load_lds_dwordx4 v[206:207], off
	v_lshl_add_u64 v[206:207], v[204:205], 0, s[68:69]
	s_mov_b32 m0, s44
	s_nop 0
	global_load_lds_dwordx4 v[206:207], off
	s_waitcnt vmcnt(8)
	s_waitcnt lgkmcnt(0)
	s_barrier
	s_setprio 1
	s_waitcnt lgkmcnt(0)
	v_mfma_f32_16x16x32_bf16 v[126:129], v[136:139], v[172:175], v[126:129]
	v_mfma_f32_16x16x32_bf16 v[122:125], v[148:151], v[172:175], v[122:125]
	v_mfma_f32_16x16x32_bf16 v[110:113], v[136:139], v[180:183], v[110:113]
	v_mfma_f32_16x16x32_bf16 v[106:109], v[148:151], v[180:183], v[106:109]
	v_mfma_f32_16x16x32_bf16 v[94:97], v[136:139], v[188:191], v[94:97]
	v_mfma_f32_16x16x32_bf16 v[90:93], v[148:151], v[188:191], v[90:93]
	v_mfma_f32_16x16x32_bf16 v[78:81], v[136:139], v[196:199], v[78:81]
	v_mfma_f32_16x16x32_bf16 v[74:77], v[148:151], v[196:199], v[74:77]
	v_mfma_f32_16x16x32_bf16 v[126:129], v[140:143], v[176:179], v[126:129]
	v_mfma_f32_16x16x32_bf16 v[122:125], v[152:155], v[176:179], v[122:125]
	v_mfma_f32_16x16x32_bf16 v[110:113], v[140:143], v[184:187], v[110:113]
	v_mfma_f32_16x16x32_bf16 v[106:109], v[152:155], v[184:187], v[106:109]
	v_mfma_f32_16x16x32_bf16 v[94:97], v[140:143], v[192:195], v[94:97]
	v_mfma_f32_16x16x32_bf16 v[90:93], v[152:155], v[192:195], v[90:93]
	v_mfma_f32_16x16x32_bf16 v[78:81], v[140:143], v[200:203], v[78:81]
	v_mfma_f32_16x16x32_bf16 v[74:77], v[152:155], v[200:203], v[74:77]
	s_setprio 0
	s_setprio 1
	v_mfma_f32_16x16x32_bf16 v[118:121], v[156:159], v[172:175], v[118:121]
	v_mfma_f32_16x16x32_bf16 v[114:117], v[164:167], v[172:175], v[114:117]
	v_mfma_f32_16x16x32_bf16 v[102:105], v[156:159], v[180:183], v[102:105]
	v_mfma_f32_16x16x32_bf16 v[98:101], v[164:167], v[180:183], v[98:101]
	v_mfma_f32_16x16x32_bf16 v[86:89], v[156:159], v[188:191], v[86:89]
	v_mfma_f32_16x16x32_bf16 v[82:85], v[164:167], v[188:191], v[82:85]
	v_mfma_f32_16x16x32_bf16 v[70:73], v[156:159], v[196:199], v[70:73]
	v_mfma_f32_16x16x32_bf16 v[66:69], v[164:167], v[196:199], v[66:69]
	v_mfma_f32_16x16x32_bf16 v[118:121], v[160:163], v[176:179], v[118:121]
	v_mfma_f32_16x16x32_bf16 v[114:117], v[168:171], v[176:179], v[114:117]
	v_mfma_f32_16x16x32_bf16 v[102:105], v[160:163], v[184:187], v[102:105]
	v_mfma_f32_16x16x32_bf16 v[98:101], v[168:171], v[184:187], v[98:101]
	v_mfma_f32_16x16x32_bf16 v[86:89], v[160:163], v[192:195], v[86:89]
	v_mfma_f32_16x16x32_bf16 v[82:85], v[168:171], v[192:195], v[82:85]
	v_mfma_f32_16x16x32_bf16 v[70:73], v[160:163], v[200:203], v[70:73]
	v_mfma_f32_16x16x32_bf16 v[66:69], v[168:171], v[200:203], v[66:69]
	s_setprio 0
	s_barrier
; #define PG8_STAGE(bufoff, gbase, voff) do { _Pragma("unroll") for (int _i = 0; _i < 2; ++_i) \
;         __builtin_amdgcn_global_load_lds((const unsigned*)((const char*)(gbase) + (size_t)_i * r64##voff + voff), (PG8_LAS unsigned*)(lds + (bufoff) + ldsw + _i * 8192), 16, 0, 0); } while (0)
; #define PG8_LDA(dst, b, h) do { _Pragma("unroll") for (int m = 0; m < 4; ++m) _Pragma("unroll") for (int k = 0; k < 2; ++k) dst[m][k] = *(const PG8_LAS bf16x8*)(lds + PG8_SA(b, h) + aoff + m * 2048 + k * 1024); } while (0)
; #define PG8_MMA(ai, bj, At, Bt) do { __builtin_amdgcn_s_setprio(1); _Pragma("unroll") for (int m = 0; m < 4; ++m) _Pragma("unroll") for (int n = 0; n < 2; ++n) _Pragma("unroll") for (int k = 0; k < 2; ++k) \
;         acc[ai][bj][m][n] = __builtin_amdgcn_mfma_f32_16x16x32_bf16(Bt[n][k], At[m][k], acc[ai][bj][m][n], 0, 0, 0); __builtin_amdgcn_s_setprio(0); } while (0)
; #define PG8_WAIT_V(n) asm volatile("s_waitcnt vmcnt(" #n ")" ::: "memory")
; #define PG8_WAIT_L(n) asm volatile("s_waitcnt lgkmcnt(" #n ")" ::: "memory")
; #define PG8_BAR __builtin_amdgcn_s_barrier()
; #define PG8_SCHED __builtin_amdgcn_sched_barrier(0)
; template <class Epi, class Sched, bool ALIGN_EPI = false, bool SP2 = false>
; __device__ __forceinline__ void gemm_phase(PG8_LAS unsigned char* lds, const Gemm g, const Sched& S, const Epi& E, int wid0) {
;     ...
;             PG8_LDA(At, 1, 1); PG8_STAGE(PG8_SB(1, 0), b3, voffB); PG8_STAGE(PG8_SB(1, 1), b3 + hstepB, voffB); PG8_STAGE(PG8_SA(1, 0), a3, voffA);
;             PG8_WAIT_V(8); PG8_WAIT_L(0); PG8_BAR; PG8_MMA(1, 0, At, B0); PG8_MMA(1, 1, At, B1); PG8_BAR; PG8_SCHED;
	s_add_i32 s28, s28, s40
	v_lshl_add_u64 v[206:207], v[144:145], 0, s[70:71]
	s_mov_b32 m0, s28
	ds_read_b128 v[172:175], v146 offset:49152
	ds_read_b128 v[176:179], v146 offset:50176
	ds_read_b128 v[180:183], v146 offset:51200
	ds_read_b128 v[184:187], v146 offset:52224
	ds_read_b128 v[188:191], v146 offset:53248
	ds_read_b128 v[192:195], v146 offset:54272
	ds_read_b128 v[196:199], v146 offset:55296
	ds_read_b128 v[200:203], v146 offset:56320
	global_load_lds_dwordx4 v[206:207], off
	v_lshl_add_u64 v[206:207], v[144:145], 0, s[72:73]
	s_add_i32 m0, s28, 0x2000
	s_add_i32 s28, s29, s40
	global_load_lds_dwordx4 v[206:207], off
	v_lshl_add_u64 v[206:207], v[144:145], 0, s[74:75]
	s_mov_b32 m0, s28
	v_lshl_add_u64 v[144:145], v[144:145], 0, s[76:77]
	global_load_lds_dwordx4 v[206:207], off
	s_add_i32 m0, s28, 0x2000
	s_nop 0
	global_load_lds_dwordx4 v[144:145], off
	v_lshl_add_u64 v[144:145], v[204:205], 0, s[70:71]
	s_mov_b32 m0, s45
	s_nop 0
	global_load_lds_dwordx4 v[144:145], off
	v_lshl_add_u64 v[144:145], v[204:205], 0, s[72:73]
	s_mov_b32 m0, s46
	s_nop 0
	global_load_lds_dwordx4 v[144:145], off
	s_waitcnt vmcnt(8)
	s_waitcnt lgkmcnt(0)
	s_barrier
	s_setprio 1
	s_waitcnt lgkmcnt(0)
	v_mfma_f32_16x16x32_bf16 v[62:65], v[136:139], v[172:175], v[62:65]
	v_mfma_f32_16x16x32_bf16 v[58:61], v[148:151], v[172:175], v[58:61]
	v_mfma_f32_16x16x32_bf16 v[46:49], v[136:139], v[180:183], v[46:49]
	v_mfma_f32_16x16x32_bf16 v[42:45], v[148:151], v[180:183], v[42:45]
	v_mfma_f32_16x16x32_bf16 v[30:33], v[136:139], v[188:191], v[30:33]
	v_mfma_f32_16x16x32_bf16 v[26:29], v[148:151], v[188:191], v[26:29]
	v_mfma_f32_16x16x32_bf16 v[14:17], v[136:139], v[196:199], v[14:17]
	v_mfma_f32_16x16x32_bf16 v[10:13], v[148:151], v[196:199], v[10:13]
	v_mfma_f32_16x16x32_bf16 v[62:65], v[140:143], v[176:179], v[62:65]
	v_mfma_f32_16x16x32_bf16 v[58:61], v[152:155], v[176:179], v[58:61]
	v_mfma_f32_16x16x32_bf16 v[46:49], v[140:143], v[184:187], v[46:49]
	v_mfma_f32_16x16x32_bf16 v[42:45], v[152:155], v[184:187], v[42:45]
	v_mfma_f32_16x16x32_bf16 v[30:33], v[140:143], v[192:195], v[30:33]
	v_mfma_f32_16x16x32_bf16 v[26:29], v[152:155], v[192:195], v[26:29]
	v_mfma_f32_16x16x32_bf16 v[14:17], v[140:143], v[200:203], v[14:17]
	v_mfma_f32_16x16x32_bf16 v[10:13], v[152:155], v[200:203], v[10:13]
	s_setprio 0
	s_setprio 1
	v_mfma_f32_16x16x32_bf16 v[54:57], v[156:159], v[172:175], v[54:57]
	v_mfma_f32_16x16x32_bf16 v[50:53], v[164:167], v[172:175], v[50:53]
	v_mfma_f32_16x16x32_bf16 v[38:41], v[156:159], v[180:183], v[38:41]
	v_mfma_f32_16x16x32_bf16 v[34:37], v[164:167], v[180:183], v[34:37]
	v_mfma_f32_16x16x32_bf16 v[22:25], v[156:159], v[188:191], v[22:25]
	v_mfma_f32_16x16x32_bf16 v[18:21], v[164:167], v[188:191], v[18:21]
	v_mfma_f32_16x16x32_bf16 v[6:9], v[156:159], v[196:199], v[6:9]
	v_mfma_f32_16x16x32_bf16 v[2:5], v[164:167], v[196:199], v[2:5]
	v_mfma_f32_16x16x32_bf16 v[54:57], v[160:163], v[176:179], v[54:57]
	v_mfma_f32_16x16x32_bf16 v[50:53], v[168:171], v[176:179], v[50:53]
	v_mfma_f32_16x16x32_bf16 v[38:41], v[160:163], v[184:187], v[38:41]
	v_mfma_f32_16x16x32_bf16 v[34:37], v[168:171], v[184:187], v[34:37]
	v_mfma_f32_16x16x32_bf16 v[22:25], v[160:163], v[192:195], v[22:25]
	v_mfma_f32_16x16x32_bf16 v[18:21], v[168:171], v[192:195], v[18:21]
	v_mfma_f32_16x16x32_bf16 v[6:9], v[160:163], v[200:203], v[6:9]
	v_mfma_f32_16x16x32_bf16 v[2:5], v[168:171], v[200:203], v[2:5]
	s_setprio 0
	s_add_i32 s79, s79, 2
	s_add_u32 s26, s26, 0x100
	s_addc_u32 s27, s27, 0
	s_add_u32 s31, s31, 0x100
	s_addc_u32 s78, s78, 0
	s_cmp_gt_u32 s79, 13
	s_barrier
	s_cbranch_scc0 .LBB0_205
	s_and_b64 vcc, exec, s[14:15]
	s_cbranch_vccz .LBB0_208
	s_barrier

; #define PG8_STAGE(bufoff, gbase, voff) do { _Pragma("unroll") for (int _i = 0; _i < 2; ++_i) \
;         __builtin_amdgcn_global_load_lds((const unsigned*)((const char*)(gbase) + (size_t)_i * r64##voff + voff), (PG8_LAS unsigned*)(lds + (bufoff) + ldsw + _i * 8192), 16, 0, 0); } while (0)
; #define PG8_LDA(dst, b, h) do { _Pragma("unroll") for (int m = 0; m < 4; ++m) _Pragma("unroll") for (int k = 0; k < 2; ++k) dst[m][k] = *(const PG8_LAS bf16x8*)(lds + PG8_SA(b, h) + aoff + m * 2048 + k * 1024); } while (0)
; #define PG8_LDB(dst, b, h) do { _Pragma("unroll") for (int n = 0; n < 2; ++n) _Pragma("unroll") for (int k = 0; k < 2; ++k) dst[n][k] = *(const PG8_LAS bf16x8*)(lds + PG8_SB(b, h) + boff + n * 2048 + k * 1024); } while (0)
; #define PG8_MMA(ai, bj, At, Bt) do { __builtin_amdgcn_s_setprio(1); _Pragma("unroll") for (int m = 0; m < 4; ++m) _Pragma("unroll") for (int n = 0; n < 2; ++n) _Pragma("unroll") for (int k = 0; k < 2; ++k) \
;         acc[ai][bj][m][n] = __builtin_amdgcn_mfma_f32_16x16x32_bf16(Bt[n][k], At[m][k], acc[ai][bj][m][n], 0, 0, 0); __builtin_amdgcn_s_setprio(0); } while (0)
; #define PG8_WAIT_V(n) asm volatile("s_waitcnt vmcnt(" #n ")" ::: "memory")
; #define PG8_WAIT_L(n) asm volatile("s_waitcnt lgkmcnt(" #n ")" ::: "memory")
; template <class Epi, class Sched, bool ALIGN_EPI = false, bool SP2 = false>
; __device__ __forceinline__ void gemm_phase(PG8_LAS unsigned char* lds, const Gemm g, const Sched& S, const Epi& E, int wid0) {
;     ...
;             const bool last = (t == nt - 2);
;             const char* a1 = cA + (size_t)(t + 1) * kstep;
;             const char* a2 = last ? nA : cA + (size_t)(t + 2) * kstep; const char* b2 = last ? nB : cB + (size_t)(t + 2) * kstep;
;             const char* a3 = a2 + kstep; const char* b3 = b2 + kstep;
;             if (last && has_next) S.a_ready(nxt);
;             if constexpr (SP2) {
;             PG8_LDB(B0, 0, 0); PG8_LDB(B1, 0, 1); PG8_SCHED; PG8_LDA(At, 0, 0); PG8_STAGE(PG8_SA(1, 1), a1 + hstepA, voffA);
;             PG8_WAIT_V(8); PG8_WAIT_L(0); PG8_BAR; PG8_MMA(0, 0, At, B0); PG8_MMA(0, 1, At, B1); PG8_BAR; PG8_SCHED;
;             PG8_LDA(At, 0, 1); PG8_STAGE(PG8_SB(0, 0), b2, voffB); PG8_STAGE(PG8_SB(0, 1), b2 + hstepB, voffB); PG8_STAGE(PG8_SA(0, 0), a2, voffA);
;             PG8_WAIT_V(8); PG8_WAIT_L(0); PG8_BAR; PG8_MMA(1, 0, At, B0); PG8_MMA(1, 1, At, B1); PG8_BAR; PG8_SCHED;
.LBB0_556:
	s_add_u32 s14, s4, 0xfffc0080
	s_addc_u32 s15, s5, -1
	s_add_i32 s63, 0, 0x10000
	s_cmp_eq_u32 vcc_hi, 12
	s_cselect_b32 s15, s79, s15
	s_cselect_b32 s14, s78, s14
	s_cselect_b32 s95, s45, s47
	s_cselect_b32 s94, vcc_lo, s46
	s_add_i32 s22, 0, 0x14000
	v_add_u32_e32 v142, s63, v1
	v_add_u32_e32 v158, s22, v1
	ds_read_b128 v[102:105], v142
	ds_read_b128 v[134:137], v142 offset:1024
	ds_read_b128 v[138:141], v142 offset:2048
	ds_read_b128 v[142:145], v142 offset:3072
	ds_read_b128 v[146:149], v158
	ds_read_b128 v[150:153], v158 offset:1024
	ds_read_b128 v[154:157], v158 offset:2048
	ds_read_b128 v[158:161], v158 offset:3072
	v_lshl_add_u64 v[194:195], s[4:5], 0, v[206:207]
	s_add_i32 m0, s17, 0xc000
	ds_read_b128 v[162:165], v248
	ds_read_b128 v[166:169], v248 offset:1024
	ds_read_b128 v[170:173], v248 offset:2048
	ds_read_b128 v[174:177], v248 offset:3072
	ds_read_b128 v[178:181], v248 offset:4096
	ds_read_b128 v[182:185], v248 offset:5120
	ds_read_b128 v[186:189], v248 offset:6144
	ds_read_b128 v[190:193], v248 offset:7168
	global_load_lds_dwordx4 v[194:195], off
	v_lshl_add_u64 v[194:195], v[194:195], 0, s[64:65]
	s_add_i32 m0, s17, 0xe000
	s_nop 0
	global_load_lds_dwordx4 v[194:195], off
	s_waitcnt vmcnt(8)
	s_waitcnt lgkmcnt(0)
	s_barrier
	s_setprio 1
	s_waitcnt lgkmcnt(0)
	v_mfma_f32_16x16x32_bf16 v[130:133], v[102:105], v[162:165], v[130:133]
	v_mfma_f32_16x16x32_bf16 v[126:129], v[138:141], v[162:165], v[126:129]
	v_mfma_f32_16x16x32_bf16 v[122:125], v[102:105], v[170:173], v[122:125]
	v_mfma_f32_16x16x32_bf16 v[118:121], v[138:141], v[170:173], v[118:121]
	v_mfma_f32_16x16x32_bf16 v[78:81], v[102:105], v[178:181], v[78:81]
	v_mfma_f32_16x16x32_bf16 v[86:89], v[138:141], v[178:181], v[86:89]
	v_mfma_f32_16x16x32_bf16 v[106:109], v[102:105], v[186:189], v[106:109]
	v_mfma_f32_16x16x32_bf16 v[90:93], v[138:141], v[186:189], v[90:93]
	v_mfma_f32_16x16x32_bf16 v[130:133], v[134:137], v[166:169], v[130:133]
	v_mfma_f32_16x16x32_bf16 v[126:129], v[142:145], v[166:169], v[126:129]
	v_mfma_f32_16x16x32_bf16 v[122:125], v[134:137], v[174:177], v[122:125]
	v_mfma_f32_16x16x32_bf16 v[118:121], v[142:145], v[174:177], v[118:121]
	v_mfma_f32_16x16x32_bf16 v[78:81], v[134:137], v[182:185], v[78:81]
	v_mfma_f32_16x16x32_bf16 v[86:89], v[142:145], v[182:185], v[86:89]
	v_mfma_f32_16x16x32_bf16 v[106:109], v[134:137], v[190:193], v[106:109]
	v_mfma_f32_16x16x32_bf16 v[90:93], v[142:145], v[190:193], v[90:93]
	s_setprio 0
	s_setprio 1
	v_mfma_f32_16x16x32_bf16 v[114:117], v[146:149], v[162:165], v[114:117]
	v_mfma_f32_16x16x32_bf16 v[110:113], v[154:157], v[162:165], v[110:113]
	v_mfma_f32_16x16x32_bf16 v[98:101], v[146:149], v[170:173], v[98:101]
	v_mfma_f32_16x16x32_bf16 v[94:97], v[154:157], v[170:173], v[94:97]
	v_mfma_f32_16x16x32_bf16 v[82:85], v[146:149], v[178:181], v[82:85]
	v_mfma_f32_16x16x32_bf16 v[70:73], v[154:157], v[178:181], v[70:73]
	v_mfma_f32_16x16x32_bf16 v[74:77], v[146:149], v[186:189], v[74:77]
	v_mfma_f32_16x16x32_bf16 v[66:69], v[154:157], v[186:189], v[66:69]
	v_mfma_f32_16x16x32_bf16 v[114:117], v[150:153], v[166:169], v[114:117]
	v_mfma_f32_16x16x32_bf16 v[110:113], v[158:161], v[166:169], v[110:113]
	v_mfma_f32_16x16x32_bf16 v[98:101], v[150:153], v[174:177], v[98:101]
	v_mfma_f32_16x16x32_bf16 v[94:97], v[158:161], v[174:177], v[94:97]
	v_mfma_f32_16x16x32_bf16 v[82:85], v[150:153], v[182:185], v[82:85]
	v_mfma_f32_16x16x32_bf16 v[70:73], v[158:161], v[182:185], v[70:73]
	v_mfma_f32_16x16x32_bf16 v[74:77], v[150:153], v[190:193], v[74:77]
	v_mfma_f32_16x16x32_bf16 v[66:69], v[158:161], v[190:193], v[66:69]
	s_setprio 0
	s_barrier
	s_add_i32 s63, s63, s40
	v_lshl_add_u64 v[194:195], s[94:95], 0, v[204:205]
	s_mov_b32 m0, s63
	ds_read_b128 v[162:165], v248 offset:16384
	ds_read_b128 v[166:169], v248 offset:17408
	ds_read_b128 v[170:173], v248 offset:18432
	ds_read_b128 v[174:177], v248 offset:19456
	ds_read_b128 v[178:181], v248 offset:20480
	ds_read_b128 v[182:185], v248 offset:21504
	ds_read_b128 v[186:189], v248 offset:22528
	ds_read_b128 v[190:193], v248 offset:23552
	global_load_lds_dwordx4 v[194:195], off
	v_lshl_add_u64 v[196:197], v[194:195], 0, s[64:65]
	s_add_i32 m0, s63, 0x2000
	s_add_i32 s22, s22, s40
	global_load_lds_dwordx4 v[196:197], off
	v_lshl_add_u64 v[196:197], v[194:195], 0, s[66:67]
	s_mov_b32 m0, s22
	s_nop 0
	global_load_lds_dwordx4 v[196:197], off
	v_lshl_add_u64 v[196:197], v[194:195], 0, s[68:69]
	s_add_i32 m0, s22, 0x2000
	s_nop 0
	global_load_lds_dwordx4 v[196:197], off
	v_lshl_add_u64 v[196:197], s[14:15], 0, v[202:203]
	s_mov_b32 m0, s17
	v_lshl_add_u64 v[198:199], v[196:197], 0, s[64:65]
	global_load_lds_dwordx4 v[196:197], off
	s_mov_b32 m0, s93
	s_nop 0
	global_load_lds_dwordx4 v[198:199], off
	s_waitcnt vmcnt(8)
	s_waitcnt lgkmcnt(0)
	s_barrier
; #define PG8_STAGE(bufoff, gbase, voff) do { _Pragma("unroll") for (int _i = 0; _i < 2; ++_i) \
;         __builtin_amdgcn_global_load_lds((const unsigned*)((const char*)(gbase) + (size_t)_i * r64##voff + voff), (PG8_LAS unsigned*)(lds + (bufoff) + ldsw + _i * 8192), 16, 0, 0); } while (0)
; #define PG8_LDA(dst, b, h) do { _Pragma("unroll") for (int m = 0; m < 4; ++m) _Pragma("unroll") for (int k = 0; k < 2; ++k) dst[m][k] = *(const PG8_LAS bf16x8*)(lds + PG8_SA(b, h) + aoff + m * 2048 + k * 1024); } while (0)
; #define PG8_LDB(dst, b, h) do { _Pragma("unroll") for (int n = 0; n < 2; ++n) _Pragma("unroll") for (int k = 0; k < 2; ++k) dst[n][k] = *(const PG8_LAS bf16x8*)(lds + PG8_SB(b, h) + boff + n * 2048 + k * 1024); } while (0)
; #define PG8_MMA(ai, bj, At, Bt) do { __builtin_amdgcn_s_setprio(1); _Pragma("unroll") for (int m = 0; m < 4; ++m) _Pragma("unroll") for (int n = 0; n < 2; ++n) _Pragma("unroll") for (int k = 0; k < 2; ++k) \
;         acc[ai][bj][m][n] = __builtin_amdgcn_mfma_f32_16x16x32_bf16(Bt[n][k], At[m][k], acc[ai][bj][m][n], 0, 0, 0); __builtin_amdgcn_s_setprio(0); } while (0)
; #define PG8_WAIT_V(n) asm volatile("s_waitcnt vmcnt(" #n ")" ::: "memory")
; #define PG8_WAIT_L(n) asm volatile("s_waitcnt lgkmcnt(" #n ")" ::: "memory")
; #define PG8_BAR __builtin_amdgcn_s_barrier()
; #define PG8_SCHED __builtin_amdgcn_sched_barrier(0)
; template <class Epi, class Sched, bool ALIGN_EPI = false, bool SP2 = false>
; __device__ __forceinline__ void gemm_phase(PG8_LAS unsigned char* lds, const Gemm g, const Sched& S, const Epi& E, int wid0) {
;     ...
;             PG8_WAIT_V(8); PG8_WAIT_L(0); PG8_BAR; PG8_MMA(1, 0, At, B0); PG8_MMA(1, 1, At, B1); PG8_BAR; PG8_SCHED;
;             PG8_LDB(B0, 1, 0); PG8_LDB(B1, 1, 1); PG8_SCHED; PG8_LDA(At, 1, 0); PG8_STAGE(PG8_SA(0, 1), a2 + hstepA, voffA);
;             PG8_WAIT_V(8); PG8_WAIT_L(0); PG8_BAR; PG8_MMA(0, 0, At, B0); PG8_MMA(0, 1, At, B1); PG8_BAR; PG8_SCHED;
	s_setprio 1
	s_waitcnt lgkmcnt(0)
	v_mfma_f32_16x16x32_bf16 v[34:37], v[102:105], v[162:165], v[34:37]
	v_mfma_f32_16x16x32_bf16 v[30:33], v[138:141], v[162:165], v[30:33]
	v_mfma_f32_16x16x32_bf16 v[22:25], v[102:105], v[170:173], v[22:25]
	v_mfma_f32_16x16x32_bf16 v[18:21], v[138:141], v[170:173], v[18:21]
	v_mfma_f32_16x16x32_bf16 v[58:61], v[102:105], v[178:181], v[58:61]
	v_mfma_f32_16x16x32_bf16 v[50:53], v[138:141], v[178:181], v[50:53]
	v_mfma_f32_16x16x32_bf16 v[62:65], v[102:105], v[186:189], v[62:65]
	v_mfma_f32_16x16x32_bf16 v[54:57], v[138:141], v[186:189], v[54:57]
	v_mfma_f32_16x16x32_bf16 v[34:37], v[134:137], v[166:169], v[34:37]
	v_mfma_f32_16x16x32_bf16 v[30:33], v[142:145], v[166:169], v[30:33]
	v_mfma_f32_16x16x32_bf16 v[22:25], v[134:137], v[174:177], v[22:25]
	v_mfma_f32_16x16x32_bf16 v[18:21], v[142:145], v[174:177], v[18:21]
	v_mfma_f32_16x16x32_bf16 v[58:61], v[134:137], v[182:185], v[58:61]
	v_mfma_f32_16x16x32_bf16 v[50:53], v[142:145], v[182:185], v[50:53]
	v_mfma_f32_16x16x32_bf16 v[62:65], v[134:137], v[190:193], v[62:65]
	v_mfma_f32_16x16x32_bf16 v[54:57], v[142:145], v[190:193], v[54:57]
	s_setprio 0
	s_setprio 1
	v_mfma_f32_16x16x32_bf16 v[14:17], v[146:149], v[162:165], v[14:17]
	v_mfma_f32_16x16x32_bf16 v[10:13], v[154:157], v[162:165], v[10:13]
	v_mfma_f32_16x16x32_bf16 v[6:9], v[146:149], v[170:173], v[6:9]
	v_mfma_f32_16x16x32_bf16 v[2:5], v[154:157], v[170:173], v[2:5]
	v_mfma_f32_16x16x32_bf16 v[42:45], v[146:149], v[178:181], v[42:45]
	v_mfma_f32_16x16x32_bf16 v[26:29], v[154:157], v[178:181], v[26:29]
	v_mfma_f32_16x16x32_bf16 v[46:49], v[146:149], v[186:189], v[46:49]
	v_mfma_f32_16x16x32_bf16 v[38:41], v[154:157], v[186:189], v[38:41]
	v_mfma_f32_16x16x32_bf16 v[14:17], v[150:153], v[166:169], v[14:17]
	v_mfma_f32_16x16x32_bf16 v[10:13], v[158:161], v[166:169], v[10:13]
	v_mfma_f32_16x16x32_bf16 v[6:9], v[150:153], v[174:177], v[6:9]
	v_mfma_f32_16x16x32_bf16 v[2:5], v[158:161], v[174:177], v[2:5]
	v_mfma_f32_16x16x32_bf16 v[42:45], v[150:153], v[182:185], v[42:45]
	v_mfma_f32_16x16x32_bf16 v[26:29], v[158:161], v[182:185], v[26:29]
	v_mfma_f32_16x16x32_bf16 v[46:49], v[150:153], v[190:193], v[46:49]
	v_mfma_f32_16x16x32_bf16 v[38:41], v[158:161], v[190:193], v[38:41]
	s_setprio 0
	s_barrier
	s_add_i32 s14, 0, 0x18000
	s_add_i32 s15, 0, 0x1c000
	v_add_u32_e32 v142, s14, v1
	v_add_u32_e32 v158, s15, v1
	ds_read_b128 v[102:105], v142
	ds_read_b128 v[134:137], v142 offset:1024
	ds_read_b128 v[138:141], v142 offset:2048
	ds_read_b128 v[142:145], v142 offset:3072
	ds_read_b128 v[146:149], v158
	ds_read_b128 v[150:153], v158 offset:1024
	ds_read_b128 v[154:157], v158 offset:2048
	ds_read_b128 v[158:161], v158 offset:3072
	s_mov_b32 m0, s20
	v_lshl_add_u64 v[198:199], v[196:197], 0, s[66:67]
	ds_read_b128 v[162:165], v248 offset:32768
	ds_read_b128 v[166:169], v248 offset:33792
	ds_read_b128 v[170:173], v248 offset:34816
	ds_read_b128 v[174:177], v248 offset:35840
	ds_read_b128 v[178:181], v248 offset:36864
	ds_read_b128 v[182:185], v248 offset:37888
	ds_read_b128 v[186:189], v248 offset:38912
	ds_read_b128 v[190:193], v248 offset:39936
	global_load_lds_dwordx4 v[198:199], off
	v_lshl_add_u64 v[198:199], v[196:197], 0, s[68:69]
	s_mov_b32 m0, s21
	s_nop 0
	global_load_lds_dwordx4 v[198:199], off
	s_waitcnt vmcnt(8)
	s_waitcnt lgkmcnt(0)
	s_barrier
	s_setprio 1
	s_waitcnt lgkmcnt(0)
	v_mfma_f32_16x16x32_bf16 v[130:133], v[102:105], v[162:165], v[130:133]
	v_mfma_f32_16x16x32_bf16 v[126:129], v[138:141], v[162:165], v[126:129]
	v_mfma_f32_16x16x32_bf16 v[122:125], v[102:105], v[170:173], v[122:125]
	v_mfma_f32_16x16x32_bf16 v[118:121], v[138:141], v[170:173], v[118:121]
	v_mfma_f32_16x16x32_bf16 v[78:81], v[102:105], v[178:181], v[78:81]
	v_mfma_f32_16x16x32_bf16 v[86:89], v[138:141], v[178:181], v[86:89]
	v_mfma_f32_16x16x32_bf16 v[106:109], v[102:105], v[186:189], v[106:109]
	v_mfma_f32_16x16x32_bf16 v[90:93], v[138:141], v[186:189], v[90:93]
	v_mfma_f32_16x16x32_bf16 v[130:133], v[134:137], v[166:169], v[130:133]
	v_mfma_f32_16x16x32_bf16 v[126:129], v[142:145], v[166:169], v[126:129]
	v_mfma_f32_16x16x32_bf16 v[122:125], v[134:137], v[174:177], v[122:125]
	v_mfma_f32_16x16x32_bf16 v[118:121], v[142:145], v[174:177], v[118:121]
	v_mfma_f32_16x16x32_bf16 v[78:81], v[134:137], v[182:185], v[78:81]
	v_mfma_f32_16x16x32_bf16 v[86:89], v[142:145], v[182:185], v[86:89]
	v_mfma_f32_16x16x32_bf16 v[106:109], v[134:137], v[190:193], v[106:109]
	v_mfma_f32_16x16x32_bf16 v[90:93], v[142:145], v[190:193], v[90:93]
	s_setprio 0
	s_setprio 1
	v_mfma_f32_16x16x32_bf16 v[114:117], v[146:149], v[162:165], v[114:117]
	v_mfma_f32_16x16x32_bf16 v[110:113], v[154:157], v[162:165], v[110:113]
	v_mfma_f32_16x16x32_bf16 v[98:101], v[146:149], v[170:173], v[98:101]
	v_mfma_f32_16x16x32_bf16 v[94:97], v[154:157], v[170:173], v[94:97]
	v_mfma_f32_16x16x32_bf16 v[82:85], v[146:149], v[178:181], v[82:85]
	v_mfma_f32_16x16x32_bf16 v[70:73], v[154:157], v[178:181], v[70:73]
	v_mfma_f32_16x16x32_bf16 v[74:77], v[146:149], v[186:189], v[74:77]
	v_mfma_f32_16x16x32_bf16 v[66:69], v[154:157], v[186:189], v[66:69]
	v_mfma_f32_16x16x32_bf16 v[114:117], v[150:153], v[166:169], v[114:117]
	v_mfma_f32_16x16x32_bf16 v[110:113], v[158:161], v[166:169], v[110:113]
	v_mfma_f32_16x16x32_bf16 v[98:101], v[150:153], v[174:177], v[98:101]
	v_mfma_f32_16x16x32_bf16 v[94:97], v[158:161], v[174:177], v[94:97]
	v_mfma_f32_16x16x32_bf16 v[82:85], v[150:153], v[182:185], v[82:85]
	v_mfma_f32_16x16x32_bf16 v[70:73], v[158:161], v[182:185], v[70:73]
	v_mfma_f32_16x16x32_bf16 v[74:77], v[150:153], v[190:193], v[74:77]
	v_mfma_f32_16x16x32_bf16 v[66:69], v[158:161], v[190:193], v[66:69]
	s_setprio 0
	s_barrier
; #define PG8_STAGE(bufoff, gbase, voff) do { _Pragma("unroll") for (int _i = 0; _i < 2; ++_i) \
;         __builtin_amdgcn_global_load_lds((const unsigned*)((const char*)(gbase) + (size_t)_i * r64##voff + voff), (PG8_LAS unsigned*)(lds + (bufoff) + ldsw + _i * 8192), 16, 0, 0); } while (0)
; #define PG8_LDA(dst, b, h) do { _Pragma("unroll") for (int m = 0; m < 4; ++m) _Pragma("unroll") for (int k = 0; k < 2; ++k) dst[m][k] = *(const PG8_LAS bf16x8*)(lds + PG8_SA(b, h) + aoff + m * 2048 + k * 1024); } while (0)
; #define PG8_MMA(ai, bj, At, Bt) do { __builtin_amdgcn_s_setprio(1); _Pragma("unroll") for (int m = 0; m < 4; ++m) _Pragma("unroll") for (int n = 0; n < 2; ++n) _Pragma("unroll") for (int k = 0; k < 2; ++k) \
;         acc[ai][bj][m][n] = __builtin_amdgcn_mfma_f32_16x16x32_bf16(Bt[n][k], At[m][k], acc[ai][bj][m][n], 0, 0, 0); __builtin_amdgcn_s_setprio(0); } while (0)
; #define PG8_WAIT_V(n) asm volatile("s_waitcnt vmcnt(" #n ")" ::: "memory")
; #define PG8_WAIT_L(n) asm volatile("s_waitcnt lgkmcnt(" #n ")" ::: "memory")
; #define PG8_BAR __builtin_amdgcn_s_barrier()
; #define PG8_SCHED __builtin_amdgcn_sched_barrier(0)
; template <class Epi, class Sched, bool ALIGN_EPI = false, bool SP2 = false>
; __device__ __forceinline__ void gemm_phase(PG8_LAS unsigned char* lds, const Gemm g, const Sched& S, const Epi& E, int wid0) {
;     ...
;             PG8_LDA(At, 1, 1); PG8_STAGE(PG8_SB(1, 0), b3, voffB); PG8_STAGE(PG8_SB(1, 1), b3 + hstepB, voffB); PG8_STAGE(PG8_SA(1, 0), a3, voffA);
;             PG8_WAIT_V(8); PG8_WAIT_L(0); PG8_BAR; PG8_MMA(1, 0, At, B0); PG8_MMA(1, 1, At, B1); PG8_BAR; PG8_SCHED;
	s_add_i32 s14, s14, s40
	v_lshl_add_u64 v[198:199], v[194:195], 0, s[70:71]
	s_mov_b32 m0, s14
	ds_read_b128 v[162:165], v248 offset:49152
	ds_read_b128 v[166:169], v248 offset:50176
	ds_read_b128 v[170:173], v248 offset:51200
	ds_read_b128 v[174:177], v248 offset:52224
	ds_read_b128 v[178:181], v248 offset:53248
	ds_read_b128 v[182:185], v248 offset:54272
	ds_read_b128 v[186:189], v248 offset:55296
	ds_read_b128 v[190:193], v248 offset:56320
	global_load_lds_dwordx4 v[198:199], off
	v_lshl_add_u64 v[198:199], v[194:195], 0, s[72:73]
	s_add_i32 m0, s14, 0x2000
	s_add_i32 s14, s15, s40
	global_load_lds_dwordx4 v[198:199], off
	v_lshl_add_u64 v[198:199], v[194:195], 0, s[74:75]
	s_mov_b32 m0, s14
	v_lshl_add_u64 v[194:195], v[194:195], 0, s[76:77]
	global_load_lds_dwordx4 v[198:199], off
	s_add_i32 m0, s14, 0x2000
	s_nop 0
	global_load_lds_dwordx4 v[194:195], off
	v_lshl_add_u64 v[194:195], v[196:197], 0, s[70:71]
	s_mov_b32 m0, s18
	s_nop 0
	global_load_lds_dwordx4 v[194:195], off
	v_lshl_add_u64 v[194:195], v[196:197], 0, s[72:73]
	s_mov_b32 m0, s19
	s_nop 0
	global_load_lds_dwordx4 v[194:195], off
	s_waitcnt vmcnt(8)
	s_waitcnt lgkmcnt(0)
	s_barrier
	s_setprio 1
	s_waitcnt lgkmcnt(0)
	v_mfma_f32_16x16x32_bf16 v[34:37], v[102:105], v[162:165], v[34:37]
	v_mfma_f32_16x16x32_bf16 v[30:33], v[138:141], v[162:165], v[30:33]
	v_mfma_f32_16x16x32_bf16 v[22:25], v[102:105], v[170:173], v[22:25]
	v_mfma_f32_16x16x32_bf16 v[18:21], v[138:141], v[170:173], v[18:21]
	v_mfma_f32_16x16x32_bf16 v[58:61], v[102:105], v[178:181], v[58:61]
	v_mfma_f32_16x16x32_bf16 v[50:53], v[138:141], v[178:181], v[50:53]
	v_mfma_f32_16x16x32_bf16 v[62:65], v[102:105], v[186:189], v[62:65]
	v_mfma_f32_16x16x32_bf16 v[54:57], v[138:141], v[186:189], v[54:57]
	v_mfma_f32_16x16x32_bf16 v[34:37], v[134:137], v[166:169], v[34:37]
	v_mfma_f32_16x16x32_bf16 v[30:33], v[142:145], v[166:169], v[30:33]
	v_mfma_f32_16x16x32_bf16 v[22:25], v[134:137], v[174:177], v[22:25]
	v_mfma_f32_16x16x32_bf16 v[18:21], v[142:145], v[174:177], v[18:21]
	v_mfma_f32_16x16x32_bf16 v[58:61], v[134:137], v[182:185], v[58:61]
	v_mfma_f32_16x16x32_bf16 v[50:53], v[142:145], v[182:185], v[50:53]
	v_mfma_f32_16x16x32_bf16 v[62:65], v[134:137], v[190:193], v[62:65]
	v_mfma_f32_16x16x32_bf16 v[54:57], v[142:145], v[190:193], v[54:57]
	s_setprio 0
	s_setprio 1
	v_mfma_f32_16x16x32_bf16 v[14:17], v[146:149], v[162:165], v[14:17]
	v_mfma_f32_16x16x32_bf16 v[10:13], v[154:157], v[162:165], v[10:13]
	v_mfma_f32_16x16x32_bf16 v[6:9], v[146:149], v[170:173], v[6:9]
	v_mfma_f32_16x16x32_bf16 v[2:5], v[154:157], v[170:173], v[2:5]
	v_mfma_f32_16x16x32_bf16 v[42:45], v[146:149], v[178:181], v[42:45]
	v_mfma_f32_16x16x32_bf16 v[26:29], v[154:157], v[178:181], v[26:29]
	v_mfma_f32_16x16x32_bf16 v[46:49], v[146:149], v[186:189], v[46:49]
	v_mfma_f32_16x16x32_bf16 v[38:41], v[154:157], v[186:189], v[38:41]
	v_mfma_f32_16x16x32_bf16 v[14:17], v[150:153], v[166:169], v[14:17]
	v_mfma_f32_16x16x32_bf16 v[10:13], v[158:161], v[166:169], v[10:13]
	v_mfma_f32_16x16x32_bf16 v[6:9], v[150:153], v[174:177], v[6:9]
	v_mfma_f32_16x16x32_bf16 v[2:5], v[158:161], v[174:177], v[2:5]
	v_mfma_f32_16x16x32_bf16 v[42:45], v[150:153], v[182:185], v[42:45]
	v_mfma_f32_16x16x32_bf16 v[26:29], v[158:161], v[182:185], v[26:29]
	v_mfma_f32_16x16x32_bf16 v[46:49], v[150:153], v[190:193], v[46:49]
	v_mfma_f32_16x16x32_bf16 v[38:41], v[158:161], v[190:193], v[38:41]
	s_setprio 0
	s_add_i32 vcc_hi, vcc_hi, 2
	s_add_u32 s4, s4, 0x100
	s_addc_u32 s5, s5, 0
	s_add_u32 s46, s46, 0x100
	s_addc_u32 s47, s47, 0
	s_cmp_gt_u32 vcc_hi, 13
	s_barrier
	s_cbranch_scc0 .LBB0_556
	s_and_b64 vcc, exec, s[34:35]
	s_cbranch_vccz .LBB0_559
	s_barrier

; #define PG8_STAGE(bufoff, gbase, voff) do { _Pragma("unroll") for (int _i = 0; _i < 2; ++_i) \
;         __builtin_amdgcn_global_load_lds((const unsigned*)((const char*)(gbase) + (size_t)_i * r64##voff + voff), (PG8_LAS unsigned*)(lds + (bufoff) + ldsw + _i * 8192), 16, 0, 0); } while (0)
; #define PG8_LDA(dst, b, h) do { _Pragma("unroll") for (int m = 0; m < 4; ++m) _Pragma("unroll") for (int k = 0; k < 2; ++k) dst[m][k] = *(const PG8_LAS bf16x8*)(lds + PG8_SA(b, h) + aoff + m * 2048 + k * 1024); } while (0)
; #define PG8_LDB(dst, b, h) do { _Pragma("unroll") for (int n = 0; n < 2; ++n) _Pragma("unroll") for (int k = 0; k < 2; ++k) dst[n][k] = *(const PG8_LAS bf16x8*)(lds + PG8_SB(b, h) + boff + n * 2048 + k * 1024); } while (0)
; #define PG8_MMA(ai, bj, At, Bt) do { __builtin_amdgcn_s_setprio(1); _Pragma("unroll") for (int m = 0; m < 4; ++m) _Pragma("unroll") for (int n = 0; n < 2; ++n) _Pragma("unroll") for (int k = 0; k < 2; ++k) \
;         acc[ai][bj][m][n] = __builtin_amdgcn_mfma_f32_16x16x32_bf16(Bt[n][k], At[m][k], acc[ai][bj][m][n], 0, 0, 0); __builtin_amdgcn_s_setprio(0); } while (0)
; #define PG8_WAIT_V(n) asm volatile("s_waitcnt vmcnt(" #n ")" ::: "memory")
; #define PG8_WAIT_L(n) asm volatile("s_waitcnt lgkmcnt(" #n ")" ::: "memory")
; template <class Epi, class Sched, bool ALIGN_EPI = false, bool SP2 = false>
; __device__ __forceinline__ void gemm_phase(PG8_LAS unsigned char* lds, const Gemm g, const Sched& S, const Epi& E, int wid0) {
;     ...
;             const bool last = (t == nt - 2);
;             const char* a1 = cA + (size_t)(t + 1) * kstep;
;             const char* a2 = last ? nA : cA + (size_t)(t + 2) * kstep; const char* b2 = last ? nB : cB + (size_t)(t + 2) * kstep;
;             const char* a3 = a2 + kstep; const char* b3 = b2 + kstep;
;             if (last && has_next) S.a_ready(nxt);
;             if constexpr (SP2) {
;             PG8_LDB(B0, 0, 0); PG8_LDB(B1, 0, 1); PG8_SCHED; PG8_LDA(At, 0, 0); PG8_STAGE(PG8_SA(1, 1), a1 + hstepA, voffA);
;             PG8_WAIT_V(8); PG8_WAIT_L(0); PG8_BAR; PG8_MMA(0, 0, At, B0); PG8_MMA(0, 1, At, B1); PG8_BAR; PG8_SCHED;
;             PG8_LDA(At, 0, 1); PG8_STAGE(PG8_SB(0, 0), b2, voffB); PG8_STAGE(PG8_SB(0, 1), b2 + hstepB, voffB); PG8_STAGE(PG8_SA(0, 0), a2, voffA);
;             PG8_WAIT_V(8); PG8_WAIT_L(0); PG8_BAR; PG8_MMA(1, 0, At, B0); PG8_MMA(1, 1, At, B1); PG8_BAR; PG8_SCHED;
.LBB0_698:
	s_add_i32 s92, s14, 2
	s_add_u32 s22, s4, 0x80
	s_addc_u32 s15, s5, 0
	s_add_i32 s63, 0, 0x10000
	s_cmp_eq_u32 s84, s14
	s_cselect_b32 s15, s59, s15
	s_cselect_b32 s14, s58, s22
	v_add_u32_e32 v142, s63, v1
	s_cselect_b32 s95, s79, s91
	s_cselect_b32 s94, s78, s90
	s_add_i32 s22, 0, 0x14000
	ds_read_b128 v[138:141], v142
	ds_read_b128 v[144:147], v142 offset:1024
	ds_read_b128 v[148:151], v142 offset:2048
	ds_read_b128 v[152:155], v142 offset:3072
	v_add_u32_e32 v142, s22, v1
	ds_read_b128 v[156:159], v142
	ds_read_b128 v[160:163], v142 offset:1024
	ds_read_b128 v[164:167], v142 offset:2048
	ds_read_b128 v[168:171], v142 offset:3072
	v_lshl_add_u64 v[204:205], s[4:5], 0, v[134:135]
	s_add_i32 m0, s19, 0xc000
	ds_read_b128 v[172:175], v143
	ds_read_b128 v[176:179], v143 offset:1024
	ds_read_b128 v[180:183], v143 offset:2048
	ds_read_b128 v[184:187], v143 offset:3072
	ds_read_b128 v[188:191], v143 offset:4096
	ds_read_b128 v[192:195], v143 offset:5120
	ds_read_b128 v[196:199], v143 offset:6144
	ds_read_b128 v[200:203], v143 offset:7168
	global_load_lds_dwordx4 v[204:205], off
	v_lshl_add_u64 v[204:205], s[4:5], 0, v[136:137]
	s_add_i32 m0, s19, 0xe000
	s_nop 0
	global_load_lds_dwordx4 v[204:205], off
	s_waitcnt vmcnt(8)
	s_waitcnt lgkmcnt(0)
	s_barrier
	s_setprio 1
	s_waitcnt lgkmcnt(0)
	v_mfma_f32_16x16x32_bf16 v[126:129], v[138:141], v[172:175], v[126:129]
	v_mfma_f32_16x16x32_bf16 v[122:125], v[148:151], v[172:175], v[122:125]
	v_mfma_f32_16x16x32_bf16 v[110:113], v[138:141], v[180:183], v[110:113]
	v_mfma_f32_16x16x32_bf16 v[106:109], v[148:151], v[180:183], v[106:109]
	v_mfma_f32_16x16x32_bf16 v[94:97], v[138:141], v[188:191], v[94:97]
	v_mfma_f32_16x16x32_bf16 v[90:93], v[148:151], v[188:191], v[90:93]
	v_mfma_f32_16x16x32_bf16 v[78:81], v[138:141], v[196:199], v[78:81]
	v_mfma_f32_16x16x32_bf16 v[74:77], v[148:151], v[196:199], v[74:77]
	v_mfma_f32_16x16x32_bf16 v[126:129], v[144:147], v[176:179], v[126:129]
	v_mfma_f32_16x16x32_bf16 v[122:125], v[152:155], v[176:179], v[122:125]
	v_mfma_f32_16x16x32_bf16 v[110:113], v[144:147], v[184:187], v[110:113]
	v_mfma_f32_16x16x32_bf16 v[106:109], v[152:155], v[184:187], v[106:109]
	v_mfma_f32_16x16x32_bf16 v[94:97], v[144:147], v[192:195], v[94:97]
	v_mfma_f32_16x16x32_bf16 v[90:93], v[152:155], v[192:195], v[90:93]
	v_mfma_f32_16x16x32_bf16 v[78:81], v[144:147], v[200:203], v[78:81]
	v_mfma_f32_16x16x32_bf16 v[74:77], v[152:155], v[200:203], v[74:77]
	s_setprio 0
	s_setprio 1
	v_mfma_f32_16x16x32_bf16 v[118:121], v[156:159], v[172:175], v[118:121]
	v_mfma_f32_16x16x32_bf16 v[114:117], v[164:167], v[172:175], v[114:117]
	v_mfma_f32_16x16x32_bf16 v[102:105], v[156:159], v[180:183], v[102:105]
	v_mfma_f32_16x16x32_bf16 v[98:101], v[164:167], v[180:183], v[98:101]
	v_mfma_f32_16x16x32_bf16 v[86:89], v[156:159], v[188:191], v[86:89]
	v_mfma_f32_16x16x32_bf16 v[82:85], v[164:167], v[188:191], v[82:85]
	v_mfma_f32_16x16x32_bf16 v[70:73], v[156:159], v[196:199], v[70:73]
	v_mfma_f32_16x16x32_bf16 v[66:69], v[164:167], v[196:199], v[66:69]
	v_mfma_f32_16x16x32_bf16 v[118:121], v[160:163], v[176:179], v[118:121]
	v_mfma_f32_16x16x32_bf16 v[114:117], v[168:171], v[176:179], v[114:117]
	v_mfma_f32_16x16x32_bf16 v[102:105], v[160:163], v[184:187], v[102:105]
	v_mfma_f32_16x16x32_bf16 v[98:101], v[168:171], v[184:187], v[98:101]
	v_mfma_f32_16x16x32_bf16 v[86:89], v[160:163], v[192:195], v[86:89]
	v_mfma_f32_16x16x32_bf16 v[82:85], v[168:171], v[192:195], v[82:85]
	v_mfma_f32_16x16x32_bf16 v[70:73], v[160:163], v[200:203], v[70:73]
	v_mfma_f32_16x16x32_bf16 v[66:69], v[168:171], v[200:203], v[66:69]
	s_setprio 0
	s_barrier
	s_add_i32 s63, s63, s17
	v_lshl_add_u64 v[204:205], s[94:95], 0, v[130:131]
	s_mov_b32 m0, s63
	ds_read_b128 v[172:175], v143 offset:16384
	ds_read_b128 v[176:179], v143 offset:17408
	ds_read_b128 v[180:183], v143 offset:18432
	ds_read_b128 v[184:187], v143 offset:19456
	ds_read_b128 v[188:191], v143 offset:20480
	ds_read_b128 v[192:195], v143 offset:21504
	ds_read_b128 v[196:199], v143 offset:22528
	ds_read_b128 v[200:203], v143 offset:23552
	global_load_lds_dwordx4 v[204:205], off
	s_add_i32 m0, s63, 0x2000
	s_add_u32 s94, s94, s49
	v_lshl_add_u64 v[206:207], v[204:205], 0, s[82:83]
	s_addc_u32 s95, s95, 0
	s_add_i32 s22, s22, s17
	global_load_lds_dwordx4 v[206:207], off
	v_lshl_add_u64 v[208:209], s[94:95], 0, v[130:131]
	s_mov_b32 m0, s22
	v_lshl_add_u64 v[210:211], v[208:209], 0, s[82:83]
	global_load_lds_dwordx4 v[208:209], off
	s_add_i32 m0, s22, 0x2000
	v_lshl_add_u64 v[212:213], s[14:15], 0, v[132:133]
	global_load_lds_dwordx4 v[210:211], off
	s_mov_b32 m0, s19
	v_lshl_add_u64 v[214:215], v[212:213], 0, s[36:37]
	global_load_lds_dwordx4 v[212:213], off
	s_mov_b32 m0, s20
	s_nop 0
	global_load_lds_dwordx4 v[214:215], off
	s_waitcnt vmcnt(8)
	s_waitcnt lgkmcnt(0)
	s_barrier
; #define PG8_STAGE(bufoff, gbase, voff) do { _Pragma("unroll") for (int _i = 0; _i < 2; ++_i) \
;         __builtin_amdgcn_global_load_lds((const unsigned*)((const char*)(gbase) + (size_t)_i * r64##voff + voff), (PG8_LAS unsigned*)(lds + (bufoff) + ldsw + _i * 8192), 16, 0, 0); } while (0)
; #define PG8_LDA(dst, b, h) do { _Pragma("unroll") for (int m = 0; m < 4; ++m) _Pragma("unroll") for (int k = 0; k < 2; ++k) dst[m][k] = *(const PG8_LAS bf16x8*)(lds + PG8_SA(b, h) + aoff + m * 2048 + k * 1024); } while (0)
; #define PG8_LDB(dst, b, h) do { _Pragma("unroll") for (int n = 0; n < 2; ++n) _Pragma("unroll") for (int k = 0; k < 2; ++k) dst[n][k] = *(const PG8_LAS bf16x8*)(lds + PG8_SB(b, h) + boff + n * 2048 + k * 1024); } while (0)
; #define PG8_MMA(ai, bj, At, Bt) do { __builtin_amdgcn_s_setprio(1); _Pragma("unroll") for (int m = 0; m < 4; ++m) _Pragma("unroll") for (int n = 0; n < 2; ++n) _Pragma("unroll") for (int k = 0; k < 2; ++k) \
;         acc[ai][bj][m][n] = __builtin_amdgcn_mfma_f32_16x16x32_bf16(Bt[n][k], At[m][k], acc[ai][bj][m][n], 0, 0, 0); __builtin_amdgcn_s_setprio(0); } while (0)
; #define PG8_WAIT_V(n) asm volatile("s_waitcnt vmcnt(" #n ")" ::: "memory")
; #define PG8_WAIT_L(n) asm volatile("s_waitcnt lgkmcnt(" #n ")" ::: "memory")
; #define PG8_BAR __builtin_amdgcn_s_barrier()
; #define PG8_SCHED __builtin_amdgcn_sched_barrier(0)
; template <class Epi, class Sched, bool ALIGN_EPI = false, bool SP2 = false>
; __device__ __forceinline__ void gemm_phase(PG8_LAS unsigned char* lds, const Gemm g, const Sched& S, const Epi& E, int wid0) {
;     ...
;             PG8_WAIT_V(8); PG8_WAIT_L(0); PG8_BAR; PG8_MMA(1, 0, At, B0); PG8_MMA(1, 1, At, B1); PG8_BAR; PG8_SCHED;
;             PG8_LDB(B0, 1, 0); PG8_LDB(B1, 1, 1); PG8_SCHED; PG8_LDA(At, 1, 0); PG8_STAGE(PG8_SA(0, 1), a2 + hstepA, voffA);
;             PG8_WAIT_V(8); PG8_WAIT_L(0); PG8_BAR; PG8_MMA(0, 0, At, B0); PG8_MMA(0, 1, At, B1); PG8_BAR; PG8_SCHED;
	s_setprio 1
	s_waitcnt lgkmcnt(0)
	v_mfma_f32_16x16x32_bf16 v[62:65], v[138:141], v[172:175], v[62:65]
	v_mfma_f32_16x16x32_bf16 v[58:61], v[148:151], v[172:175], v[58:61]
	v_mfma_f32_16x16x32_bf16 v[46:49], v[138:141], v[180:183], v[46:49]
	v_mfma_f32_16x16x32_bf16 v[42:45], v[148:151], v[180:183], v[42:45]
	v_mfma_f32_16x16x32_bf16 v[30:33], v[138:141], v[188:191], v[30:33]
	v_mfma_f32_16x16x32_bf16 v[26:29], v[148:151], v[188:191], v[26:29]
	v_mfma_f32_16x16x32_bf16 v[14:17], v[138:141], v[196:199], v[14:17]
	v_mfma_f32_16x16x32_bf16 v[10:13], v[148:151], v[196:199], v[10:13]
	v_mfma_f32_16x16x32_bf16 v[62:65], v[144:147], v[176:179], v[62:65]
	v_mfma_f32_16x16x32_bf16 v[58:61], v[152:155], v[176:179], v[58:61]
	v_mfma_f32_16x16x32_bf16 v[46:49], v[144:147], v[184:187], v[46:49]
	v_mfma_f32_16x16x32_bf16 v[42:45], v[152:155], v[184:187], v[42:45]
	v_mfma_f32_16x16x32_bf16 v[30:33], v[144:147], v[192:195], v[30:33]
	v_mfma_f32_16x16x32_bf16 v[26:29], v[152:155], v[192:195], v[26:29]
	v_mfma_f32_16x16x32_bf16 v[14:17], v[144:147], v[200:203], v[14:17]
	v_mfma_f32_16x16x32_bf16 v[10:13], v[152:155], v[200:203], v[10:13]
	s_setprio 0
	s_setprio 1
	v_mfma_f32_16x16x32_bf16 v[54:57], v[156:159], v[172:175], v[54:57]
	v_mfma_f32_16x16x32_bf16 v[50:53], v[164:167], v[172:175], v[50:53]
	v_mfma_f32_16x16x32_bf16 v[38:41], v[156:159], v[180:183], v[38:41]
	v_mfma_f32_16x16x32_bf16 v[34:37], v[164:167], v[180:183], v[34:37]
	v_mfma_f32_16x16x32_bf16 v[22:25], v[156:159], v[188:191], v[22:25]
	v_mfma_f32_16x16x32_bf16 v[18:21], v[164:167], v[188:191], v[18:21]
	v_mfma_f32_16x16x32_bf16 v[6:9], v[156:159], v[196:199], v[6:9]
	v_mfma_f32_16x16x32_bf16 v[2:5], v[164:167], v[196:199], v[2:5]
	v_mfma_f32_16x16x32_bf16 v[54:57], v[160:163], v[176:179], v[54:57]
	v_mfma_f32_16x16x32_bf16 v[50:53], v[168:171], v[176:179], v[50:53]
	v_mfma_f32_16x16x32_bf16 v[38:41], v[160:163], v[184:187], v[38:41]
	v_mfma_f32_16x16x32_bf16 v[34:37], v[168:171], v[184:187], v[34:37]
	v_mfma_f32_16x16x32_bf16 v[22:25], v[160:163], v[192:195], v[22:25]
	v_mfma_f32_16x16x32_bf16 v[18:21], v[168:171], v[192:195], v[18:21]
	v_mfma_f32_16x16x32_bf16 v[6:9], v[160:163], v[200:203], v[6:9]
	v_mfma_f32_16x16x32_bf16 v[2:5], v[168:171], v[200:203], v[2:5]
	s_setprio 0
	s_barrier
	s_add_i32 s22, 0, 0x18000
	v_add_u32_e32 v142, s22, v1
	s_add_i32 s63, 0, 0x1c000
	ds_read_b128 v[138:141], v142
	ds_read_b128 v[144:147], v142 offset:1024
	ds_read_b128 v[148:151], v142 offset:2048
	ds_read_b128 v[152:155], v142 offset:3072
	v_add_u32_e32 v142, s63, v1
	ds_read_b128 v[156:159], v142
	ds_read_b128 v[160:163], v142 offset:1024
	ds_read_b128 v[164:167], v142 offset:2048
	ds_read_b128 v[168:171], v142 offset:3072
	s_add_u32 s14, s14, s60
	s_addc_u32 s15, s15, 0
	s_mov_b32 m0, s21
	v_lshl_add_u64 v[216:217], s[14:15], 0, v[132:133]
	ds_read_b128 v[172:175], v143 offset:32768
	ds_read_b128 v[176:179], v143 offset:33792
	ds_read_b128 v[180:183], v143 offset:34816
	ds_read_b128 v[184:187], v143 offset:35840
	ds_read_b128 v[188:191], v143 offset:36864
	ds_read_b128 v[192:195], v143 offset:37888
	ds_read_b128 v[196:199], v143 offset:38912
	ds_read_b128 v[200:203], v143 offset:39936
	global_load_lds_dwordx4 v[216:217], off
	v_lshl_add_u64 v[216:217], v[216:217], 0, s[36:37]
	s_mov_b32 m0, s23
	s_nop 0
	global_load_lds_dwordx4 v[216:217], off
	s_waitcnt vmcnt(8)
	s_waitcnt lgkmcnt(0)
	s_barrier
	s_setprio 1
	s_waitcnt lgkmcnt(0)
	v_mfma_f32_16x16x32_bf16 v[126:129], v[138:141], v[172:175], v[126:129]
	v_mfma_f32_16x16x32_bf16 v[122:125], v[148:151], v[172:175], v[122:125]
	v_mfma_f32_16x16x32_bf16 v[110:113], v[138:141], v[180:183], v[110:113]
	v_mfma_f32_16x16x32_bf16 v[106:109], v[148:151], v[180:183], v[106:109]
	v_mfma_f32_16x16x32_bf16 v[94:97], v[138:141], v[188:191], v[94:97]
	v_mfma_f32_16x16x32_bf16 v[90:93], v[148:151], v[188:191], v[90:93]
	v_mfma_f32_16x16x32_bf16 v[78:81], v[138:141], v[196:199], v[78:81]
	v_mfma_f32_16x16x32_bf16 v[74:77], v[148:151], v[196:199], v[74:77]
	v_mfma_f32_16x16x32_bf16 v[126:129], v[144:147], v[176:179], v[126:129]
	v_mfma_f32_16x16x32_bf16 v[122:125], v[152:155], v[176:179], v[122:125]
	v_mfma_f32_16x16x32_bf16 v[110:113], v[144:147], v[184:187], v[110:113]
	v_mfma_f32_16x16x32_bf16 v[106:109], v[152:155], v[184:187], v[106:109]
	v_mfma_f32_16x16x32_bf16 v[94:97], v[144:147], v[192:195], v[94:97]
	v_mfma_f32_16x16x32_bf16 v[90:93], v[152:155], v[192:195], v[90:93]
	v_mfma_f32_16x16x32_bf16 v[78:81], v[144:147], v[200:203], v[78:81]
	v_mfma_f32_16x16x32_bf16 v[74:77], v[152:155], v[200:203], v[74:77]
	s_setprio 0
	s_setprio 1
	v_mfma_f32_16x16x32_bf16 v[118:121], v[156:159], v[172:175], v[118:121]
	v_mfma_f32_16x16x32_bf16 v[114:117], v[164:167], v[172:175], v[114:117]
	v_mfma_f32_16x16x32_bf16 v[102:105], v[156:159], v[180:183], v[102:105]
	v_mfma_f32_16x16x32_bf16 v[98:101], v[164:167], v[180:183], v[98:101]
	v_mfma_f32_16x16x32_bf16 v[86:89], v[156:159], v[188:191], v[86:89]
	v_mfma_f32_16x16x32_bf16 v[82:85], v[164:167], v[188:191], v[82:85]
	v_mfma_f32_16x16x32_bf16 v[70:73], v[156:159], v[196:199], v[70:73]
	v_mfma_f32_16x16x32_bf16 v[66:69], v[164:167], v[196:199], v[66:69]
	v_mfma_f32_16x16x32_bf16 v[118:121], v[160:163], v[176:179], v[118:121]
	v_mfma_f32_16x16x32_bf16 v[114:117], v[168:171], v[176:179], v[114:117]
	v_mfma_f32_16x16x32_bf16 v[102:105], v[160:163], v[184:187], v[102:105]
	v_mfma_f32_16x16x32_bf16 v[98:101], v[168:171], v[184:187], v[98:101]
	v_mfma_f32_16x16x32_bf16 v[86:89], v[160:163], v[192:195], v[86:89]
	v_mfma_f32_16x16x32_bf16 v[82:85], v[168:171], v[192:195], v[82:85]
	v_mfma_f32_16x16x32_bf16 v[70:73], v[160:163], v[200:203], v[70:73]
	v_mfma_f32_16x16x32_bf16 v[66:69], v[168:171], v[200:203], v[66:69]
	s_setprio 0
	s_barrier
; #define PG8_STAGE(bufoff, gbase, voff) do { _Pragma("unroll") for (int _i = 0; _i < 2; ++_i) \
;         __builtin_amdgcn_global_load_lds((const unsigned*)((const char*)(gbase) + (size_t)_i * r64##voff + voff), (PG8_LAS unsigned*)(lds + (bufoff) + ldsw + _i * 8192), 16, 0, 0); } while (0)
; #define PG8_LDA(dst, b, h) do { _Pragma("unroll") for (int m = 0; m < 4; ++m) _Pragma("unroll") for (int k = 0; k < 2; ++k) dst[m][k] = *(const PG8_LAS bf16x8*)(lds + PG8_SA(b, h) + aoff + m * 2048 + k * 1024); } while (0)
; #define PG8_MMA(ai, bj, At, Bt) do { __builtin_amdgcn_s_setprio(1); _Pragma("unroll") for (int m = 0; m < 4; ++m) _Pragma("unroll") for (int n = 0; n < 2; ++n) _Pragma("unroll") for (int k = 0; k < 2; ++k) \
;         acc[ai][bj][m][n] = __builtin_amdgcn_mfma_f32_16x16x32_bf16(Bt[n][k], At[m][k], acc[ai][bj][m][n], 0, 0, 0); __builtin_amdgcn_s_setprio(0); } while (0)
; #define PG8_WAIT_V(n) asm volatile("s_waitcnt vmcnt(" #n ")" ::: "memory")
; #define PG8_WAIT_L(n) asm volatile("s_waitcnt lgkmcnt(" #n ")" ::: "memory")
; #define PG8_BAR __builtin_amdgcn_s_barrier()
; #define PG8_SCHED __builtin_amdgcn_sched_barrier(0)
; template <class Epi, class Sched, bool ALIGN_EPI = false, bool SP2 = false>
; __device__ __forceinline__ void gemm_phase(PG8_LAS unsigned char* lds, const Gemm g, const Sched& S, const Epi& E, int wid0) {
;     ...
;             PG8_LDA(At, 1, 1); PG8_STAGE(PG8_SB(1, 0), b3, voffB); PG8_STAGE(PG8_SB(1, 1), b3 + hstepB, voffB); PG8_STAGE(PG8_SA(1, 0), a3, voffA);
;             PG8_WAIT_V(8); PG8_WAIT_L(0); PG8_BAR; PG8_MMA(1, 0, At, B0); PG8_MMA(1, 1, At, B1); PG8_BAR; PG8_SCHED;
	s_add_i32 s14, s22, s17
	v_lshl_add_u64 v[204:205], v[204:205], 0, s[70:71]
	s_mov_b32 m0, s14
	ds_read_b128 v[172:175], v143 offset:49152
	ds_read_b128 v[176:179], v143 offset:50176
	ds_read_b128 v[180:183], v143 offset:51200
	ds_read_b128 v[184:187], v143 offset:52224
	ds_read_b128 v[188:191], v143 offset:53248
	ds_read_b128 v[192:195], v143 offset:54272
	ds_read_b128 v[196:199], v143 offset:55296
	ds_read_b128 v[200:203], v143 offset:56320
	global_load_lds_dwordx4 v[204:205], off
	v_lshl_add_u64 v[204:205], v[206:207], 0, s[70:71]
	s_add_i32 m0, s14, 0x2000
	s_add_i32 s14, s63, s17
	global_load_lds_dwordx4 v[204:205], off
	v_lshl_add_u64 v[204:205], v[208:209], 0, s[70:71]
	s_mov_b32 m0, s14
	s_nop 0
	global_load_lds_dwordx4 v[204:205], off
	v_lshl_add_u64 v[204:205], v[210:211], 0, s[70:71]
	s_add_i32 m0, s14, 0x2000
	s_nop 0
	global_load_lds_dwordx4 v[204:205], off
	v_lshl_add_u64 v[204:205], v[212:213], 0, s[70:71]
	s_mov_b32 m0, s56
	s_nop 0
	global_load_lds_dwordx4 v[204:205], off
	v_lshl_add_u64 v[204:205], v[214:215], 0, s[70:71]
	s_mov_b32 m0, s57
	s_nop 0
	global_load_lds_dwordx4 v[204:205], off
	s_waitcnt vmcnt(8)
	s_waitcnt lgkmcnt(0)
	s_barrier
	s_setprio 1
	s_waitcnt lgkmcnt(0)
	v_mfma_f32_16x16x32_bf16 v[62:65], v[138:141], v[172:175], v[62:65]
	v_mfma_f32_16x16x32_bf16 v[58:61], v[148:151], v[172:175], v[58:61]
	v_mfma_f32_16x16x32_bf16 v[46:49], v[138:141], v[180:183], v[46:49]
	v_mfma_f32_16x16x32_bf16 v[42:45], v[148:151], v[180:183], v[42:45]
	v_mfma_f32_16x16x32_bf16 v[30:33], v[138:141], v[188:191], v[30:33]
	v_mfma_f32_16x16x32_bf16 v[26:29], v[148:151], v[188:191], v[26:29]
	v_mfma_f32_16x16x32_bf16 v[14:17], v[138:141], v[196:199], v[14:17]
	v_mfma_f32_16x16x32_bf16 v[10:13], v[148:151], v[196:199], v[10:13]
	v_mfma_f32_16x16x32_bf16 v[62:65], v[144:147], v[176:179], v[62:65]
	v_mfma_f32_16x16x32_bf16 v[58:61], v[152:155], v[176:179], v[58:61]
	v_mfma_f32_16x16x32_bf16 v[46:49], v[144:147], v[184:187], v[46:49]
	v_mfma_f32_16x16x32_bf16 v[42:45], v[152:155], v[184:187], v[42:45]
	v_mfma_f32_16x16x32_bf16 v[30:33], v[144:147], v[192:195], v[30:33]
	v_mfma_f32_16x16x32_bf16 v[26:29], v[152:155], v[192:195], v[26:29]
	v_mfma_f32_16x16x32_bf16 v[14:17], v[144:147], v[200:203], v[14:17]
	v_mfma_f32_16x16x32_bf16 v[10:13], v[152:155], v[200:203], v[10:13]
	s_setprio 0
	s_setprio 1
	v_mfma_f32_16x16x32_bf16 v[54:57], v[156:159], v[172:175], v[54:57]
	v_mfma_f32_16x16x32_bf16 v[50:53], v[164:167], v[172:175], v[50:53]
	v_mfma_f32_16x16x32_bf16 v[38:41], v[156:159], v[180:183], v[38:41]
	v_mfma_f32_16x16x32_bf16 v[34:37], v[164:167], v[180:183], v[34:37]
	v_mfma_f32_16x16x32_bf16 v[22:25], v[156:159], v[188:191], v[22:25]
	v_mfma_f32_16x16x32_bf16 v[18:21], v[164:167], v[188:191], v[18:21]
	v_mfma_f32_16x16x32_bf16 v[6:9], v[156:159], v[196:199], v[6:9]
	v_mfma_f32_16x16x32_bf16 v[2:5], v[164:167], v[196:199], v[2:5]
	v_mfma_f32_16x16x32_bf16 v[54:57], v[160:163], v[176:179], v[54:57]
	v_mfma_f32_16x16x32_bf16 v[50:53], v[168:171], v[176:179], v[50:53]
	v_mfma_f32_16x16x32_bf16 v[38:41], v[160:163], v[184:187], v[38:41]
	v_mfma_f32_16x16x32_bf16 v[34:37], v[168:171], v[184:187], v[34:37]
	v_mfma_f32_16x16x32_bf16 v[22:25], v[160:163], v[192:195], v[22:25]
	v_mfma_f32_16x16x32_bf16 v[18:21], v[168:171], v[192:195], v[18:21]
	v_mfma_f32_16x16x32_bf16 v[6:9], v[160:163], v[200:203], v[6:9]
	v_mfma_f32_16x16x32_bf16 v[2:5], v[168:171], v[200:203], v[2:5]
	s_setprio 0
	s_add_u32 s4, s4, 0x100
	s_addc_u32 s5, s5, 0
	s_add_u32 s90, s90, 0x100
	s_addc_u32 s91, s91, 0
	s_cmp_ge_u32 s92, s40
	s_mov_b32 s14, s92
	s_barrier
	s_cbranch_scc0 .LBB0_698
	s_and_b64 vcc, exec, s[44:45]
	s_cbranch_vccz .LBB0_701
	s_barrier

; #define PG8_STAGE(bufoff, gbase, voff) do { _Pragma("unroll") for (int _i = 0; _i < 2; ++_i) \
;         __builtin_amdgcn_global_load_lds((const unsigned*)((const char*)(gbase) + (size_t)_i * r64##voff + voff), (PG8_LAS unsigned*)(lds + (bufoff) + ldsw + _i * 8192), 16, 0, 0); } while (0)
; #define PG8_LDA(dst, b, h) do { _Pragma("unroll") for (int m = 0; m < 4; ++m) _Pragma("unroll") for (int k = 0; k < 2; ++k) dst[m][k] = *(const PG8_LAS bf16x8*)(lds + PG8_SA(b, h) + aoff + m * 2048 + k * 1024); } while (0)
; #define PG8_LDB(dst, b, h) do { _Pragma("unroll") for (int n = 0; n < 2; ++n) _Pragma("unroll") for (int k = 0; k < 2; ++k) dst[n][k] = *(const PG8_LAS bf16x8*)(lds + PG8_SB(b, h) + boff + n * 2048 + k * 1024); } while (0)
; #define PG8_MMA(ai, bj, At, Bt) do { __builtin_amdgcn_s_setprio(1); _Pragma("unroll") for (int m = 0; m < 4; ++m) _Pragma("unroll") for (int n = 0; n < 2; ++n) _Pragma("unroll") for (int k = 0; k < 2; ++k) \
;         acc[ai][bj][m][n] = __builtin_amdgcn_mfma_f32_16x16x32_bf16(Bt[n][k], At[m][k], acc[ai][bj][m][n], 0, 0, 0); __builtin_amdgcn_s_setprio(0); } while (0)
; #define PG8_WAIT_V(n) asm volatile("s_waitcnt vmcnt(" #n ")" ::: "memory")
; #define PG8_WAIT_L(n) asm volatile("s_waitcnt lgkmcnt(" #n ")" ::: "memory")
; template <class Epi, class Sched, bool ALIGN_EPI = false, bool SP2 = false>
; __device__ __forceinline__ void gemm_phase(PG8_LAS unsigned char* lds, const Gemm g, const Sched& S, const Epi& E, int wid0) {
;     ...
;             const bool last = (t == nt - 2);
;             const char* a1 = cA + (size_t)(t + 1) * kstep;
;             const char* a2 = last ? nA : cA + (size_t)(t + 2) * kstep; const char* b2 = last ? nB : cB + (size_t)(t + 2) * kstep;
;             const char* a3 = a2 + kstep; const char* b3 = b2 + kstep;
;             if (last && has_next) S.a_ready(nxt);
;             if constexpr (SP2) {
;             PG8_LDB(B0, 0, 0); PG8_LDB(B1, 0, 1); PG8_SCHED; PG8_LDA(At, 0, 0); PG8_STAGE(PG8_SA(1, 1), a1 + hstepA, voffA);
;             PG8_WAIT_V(8); PG8_WAIT_L(0); PG8_BAR; PG8_MMA(0, 0, At, B0); PG8_MMA(0, 1, At, B1); PG8_BAR; PG8_SCHED;
;             PG8_LDA(At, 0, 1); PG8_STAGE(PG8_SB(0, 0), b2, voffB); PG8_STAGE(PG8_SB(0, 1), b2 + hstepB, voffB); PG8_STAGE(PG8_SA(0, 0), a2, voffA);
;             PG8_WAIT_V(8); PG8_WAIT_L(0); PG8_BAR; PG8_MMA(1, 0, At, B0); PG8_MMA(1, 1, At, B1); PG8_BAR; PG8_SCHED;
.LBB0_829:
	s_add_i32 s44, s14, 2
	s_mov_b32 s45, s87
	s_or_b32 s86, s14, 1
	s_lshl_b64 s[46:47], s[44:45], 7
	s_cmp_lg_u32 s14, s40
	s_cselect_b32 s41, s46, 0
	s_cselect_b32 s22, s47, 0
	s_add_u32 s14, s10, s41
	s_addc_u32 s15, s11, s22
	s_add_i32 s43, 0, 0x10000
	s_add_u32 s46, s8, s41
	v_add_u32_e32 v137, s43, v1
	s_addc_u32 s47, s9, s22
	s_add_i32 s22, 0, 0x14000
	ds_read_b128 v[138:141], v137
	ds_read_b128 v[142:145], v137 offset:1024
	ds_read_b128 v[146:149], v137 offset:2048
	ds_read_b128 v[150:153], v137 offset:3072
	v_add_u32_e32 v137, s22, v1
	ds_read_b128 v[154:157], v137
	ds_read_b128 v[158:161], v137 offset:1024
	ds_read_b128 v[162:165], v137 offset:2048
	ds_read_b128 v[166:169], v137 offset:3072
	s_lshl_b64 s[56:57], s[86:87], 7
	v_lshl_add_u64 v[202:203], v[134:135], 0, s[56:57]
	s_add_i32 m0, s0, 0xc000
	ds_read_b128 v[170:173], v136
	ds_read_b128 v[174:177], v136 offset:1024
	ds_read_b128 v[178:181], v136 offset:2048
	ds_read_b128 v[182:185], v136 offset:3072
	ds_read_b128 v[186:189], v136 offset:4096
	ds_read_b128 v[190:193], v136 offset:5120
	ds_read_b128 v[194:197], v136 offset:6144
	ds_read_b128 v[198:201], v136 offset:7168
	global_load_lds_dwordx4 v[202:203], off
	v_lshl_add_u64 v[202:203], v[202:203], 0, s[36:37]
	s_add_i32 m0, s0, 0xe000
	s_nop 0
	global_load_lds_dwordx4 v[202:203], off
	s_waitcnt vmcnt(8)
	s_waitcnt lgkmcnt(0)
	s_barrier
	s_setprio 1
	s_waitcnt lgkmcnt(0)
	v_mfma_f32_16x16x32_bf16 v[126:129], v[138:141], v[170:173], v[126:129]
	v_mfma_f32_16x16x32_bf16 v[122:125], v[146:149], v[170:173], v[122:125]
	v_mfma_f32_16x16x32_bf16 v[110:113], v[138:141], v[178:181], v[110:113]
	v_mfma_f32_16x16x32_bf16 v[106:109], v[146:149], v[178:181], v[106:109]
	v_mfma_f32_16x16x32_bf16 v[94:97], v[138:141], v[186:189], v[94:97]
	v_mfma_f32_16x16x32_bf16 v[90:93], v[146:149], v[186:189], v[90:93]
	v_mfma_f32_16x16x32_bf16 v[78:81], v[138:141], v[194:197], v[78:81]
	v_mfma_f32_16x16x32_bf16 v[74:77], v[146:149], v[194:197], v[74:77]
	v_mfma_f32_16x16x32_bf16 v[126:129], v[142:145], v[174:177], v[126:129]
	v_mfma_f32_16x16x32_bf16 v[122:125], v[150:153], v[174:177], v[122:125]
	v_mfma_f32_16x16x32_bf16 v[110:113], v[142:145], v[182:185], v[110:113]
	v_mfma_f32_16x16x32_bf16 v[106:109], v[150:153], v[182:185], v[106:109]
	v_mfma_f32_16x16x32_bf16 v[94:97], v[142:145], v[190:193], v[94:97]
	v_mfma_f32_16x16x32_bf16 v[90:93], v[150:153], v[190:193], v[90:93]
	v_mfma_f32_16x16x32_bf16 v[78:81], v[142:145], v[198:201], v[78:81]
	v_mfma_f32_16x16x32_bf16 v[74:77], v[150:153], v[198:201], v[74:77]
	s_setprio 0
	s_setprio 1
	v_mfma_f32_16x16x32_bf16 v[118:121], v[154:157], v[170:173], v[118:121]
	v_mfma_f32_16x16x32_bf16 v[114:117], v[162:165], v[170:173], v[114:117]
	v_mfma_f32_16x16x32_bf16 v[102:105], v[154:157], v[178:181], v[102:105]
	v_mfma_f32_16x16x32_bf16 v[98:101], v[162:165], v[178:181], v[98:101]
	v_mfma_f32_16x16x32_bf16 v[86:89], v[154:157], v[186:189], v[86:89]
	v_mfma_f32_16x16x32_bf16 v[82:85], v[162:165], v[186:189], v[82:85]
	v_mfma_f32_16x16x32_bf16 v[70:73], v[154:157], v[194:197], v[70:73]
	v_mfma_f32_16x16x32_bf16 v[66:69], v[162:165], v[194:197], v[66:69]
	v_mfma_f32_16x16x32_bf16 v[118:121], v[158:161], v[174:177], v[118:121]
	v_mfma_f32_16x16x32_bf16 v[114:117], v[166:169], v[174:177], v[114:117]
	v_mfma_f32_16x16x32_bf16 v[102:105], v[158:161], v[182:185], v[102:105]
	v_mfma_f32_16x16x32_bf16 v[98:101], v[166:169], v[182:185], v[98:101]
	v_mfma_f32_16x16x32_bf16 v[86:89], v[158:161], v[190:193], v[86:89]
	v_mfma_f32_16x16x32_bf16 v[82:85], v[166:169], v[190:193], v[82:85]
	v_mfma_f32_16x16x32_bf16 v[70:73], v[158:161], v[198:201], v[70:73]
	v_mfma_f32_16x16x32_bf16 v[66:69], v[166:169], v[198:201], v[66:69]
	s_setprio 0
	s_barrier
	s_add_i32 s41, s43, s20
	v_lshl_add_u64 v[202:203], s[46:47], 0, v[130:131]
	s_mov_b32 m0, s41
	ds_read_b128 v[170:173], v136 offset:16384
	ds_read_b128 v[174:177], v136 offset:17408
	ds_read_b128 v[178:181], v136 offset:18432
	ds_read_b128 v[182:185], v136 offset:19456
	ds_read_b128 v[186:189], v136 offset:20480
	ds_read_b128 v[190:193], v136 offset:21504
	ds_read_b128 v[194:197], v136 offset:22528
	ds_read_b128 v[198:201], v136 offset:23552
	global_load_lds_dwordx4 v[202:203], off
	s_add_i32 m0, s41, 0x2000
	s_add_u32 s46, s46, s49
	v_lshl_add_u64 v[204:205], v[202:203], 0, s[82:83]
	s_addc_u32 s47, s47, 0
	s_add_i32 s22, s22, s20
	global_load_lds_dwordx4 v[204:205], off
	v_lshl_add_u64 v[206:207], s[46:47], 0, v[130:131]
	s_mov_b32 m0, s22
	v_lshl_add_u64 v[208:209], v[206:207], 0, s[82:83]
	global_load_lds_dwordx4 v[206:207], off
	s_add_i32 m0, s22, 0x2000
	v_lshl_add_u64 v[210:211], s[14:15], 0, v[132:133]
	global_load_lds_dwordx4 v[208:209], off
	s_mov_b32 m0, s0
	v_lshl_add_u64 v[212:213], v[210:211], 0, s[36:37]
	global_load_lds_dwordx4 v[210:211], off
	s_mov_b32 m0, s6
	s_nop 0
	global_load_lds_dwordx4 v[212:213], off
	s_waitcnt vmcnt(8)
	s_waitcnt lgkmcnt(0)
	s_barrier
; #define PG8_STAGE(bufoff, gbase, voff) do { _Pragma("unroll") for (int _i = 0; _i < 2; ++_i) \
;         __builtin_amdgcn_global_load_lds((const unsigned*)((const char*)(gbase) + (size_t)_i * r64##voff + voff), (PG8_LAS unsigned*)(lds + (bufoff) + ldsw + _i * 8192), 16, 0, 0); } while (0)
; #define PG8_LDA(dst, b, h) do { _Pragma("unroll") for (int m = 0; m < 4; ++m) _Pragma("unroll") for (int k = 0; k < 2; ++k) dst[m][k] = *(const PG8_LAS bf16x8*)(lds + PG8_SA(b, h) + aoff + m * 2048 + k * 1024); } while (0)
; #define PG8_LDB(dst, b, h) do { _Pragma("unroll") for (int n = 0; n < 2; ++n) _Pragma("unroll") for (int k = 0; k < 2; ++k) dst[n][k] = *(const PG8_LAS bf16x8*)(lds + PG8_SB(b, h) + boff + n * 2048 + k * 1024); } while (0)
; #define PG8_MMA(ai, bj, At, Bt) do { __builtin_amdgcn_s_setprio(1); _Pragma("unroll") for (int m = 0; m < 4; ++m) _Pragma("unroll") for (int n = 0; n < 2; ++n) _Pragma("unroll") for (int k = 0; k < 2; ++k) \
;         acc[ai][bj][m][n] = __builtin_amdgcn_mfma_f32_16x16x32_bf16(Bt[n][k], At[m][k], acc[ai][bj][m][n], 0, 0, 0); __builtin_amdgcn_s_setprio(0); } while (0)
; #define PG8_WAIT_V(n) asm volatile("s_waitcnt vmcnt(" #n ")" ::: "memory")
; #define PG8_WAIT_L(n) asm volatile("s_waitcnt lgkmcnt(" #n ")" ::: "memory")
; #define PG8_BAR __builtin_amdgcn_s_barrier()
; #define PG8_SCHED __builtin_amdgcn_sched_barrier(0)
; template <class Epi, class Sched, bool ALIGN_EPI = false, bool SP2 = false>
; __device__ __forceinline__ void gemm_phase(PG8_LAS unsigned char* lds, const Gemm g, const Sched& S, const Epi& E, int wid0) {
;     ...
;             PG8_WAIT_V(8); PG8_WAIT_L(0); PG8_BAR; PG8_MMA(1, 0, At, B0); PG8_MMA(1, 1, At, B1); PG8_BAR; PG8_SCHED;
;             PG8_LDB(B0, 1, 0); PG8_LDB(B1, 1, 1); PG8_SCHED; PG8_LDA(At, 1, 0); PG8_STAGE(PG8_SA(0, 1), a2 + hstepA, voffA);
;             PG8_WAIT_V(8); PG8_WAIT_L(0); PG8_BAR; PG8_MMA(0, 0, At, B0); PG8_MMA(0, 1, At, B1); PG8_BAR; PG8_SCHED;
	s_setprio 1
	s_waitcnt lgkmcnt(0)
	v_mfma_f32_16x16x32_bf16 v[62:65], v[138:141], v[170:173], v[62:65]
	v_mfma_f32_16x16x32_bf16 v[58:61], v[146:149], v[170:173], v[58:61]
	v_mfma_f32_16x16x32_bf16 v[46:49], v[138:141], v[178:181], v[46:49]
	v_mfma_f32_16x16x32_bf16 v[42:45], v[146:149], v[178:181], v[42:45]
	v_mfma_f32_16x16x32_bf16 v[30:33], v[138:141], v[186:189], v[30:33]
	v_mfma_f32_16x16x32_bf16 v[26:29], v[146:149], v[186:189], v[26:29]
	v_mfma_f32_16x16x32_bf16 v[14:17], v[138:141], v[194:197], v[14:17]
	v_mfma_f32_16x16x32_bf16 v[10:13], v[146:149], v[194:197], v[10:13]
	v_mfma_f32_16x16x32_bf16 v[62:65], v[142:145], v[174:177], v[62:65]
	v_mfma_f32_16x16x32_bf16 v[58:61], v[150:153], v[174:177], v[58:61]
	v_mfma_f32_16x16x32_bf16 v[46:49], v[142:145], v[182:185], v[46:49]
	v_mfma_f32_16x16x32_bf16 v[42:45], v[150:153], v[182:185], v[42:45]
	v_mfma_f32_16x16x32_bf16 v[30:33], v[142:145], v[190:193], v[30:33]
	v_mfma_f32_16x16x32_bf16 v[26:29], v[150:153], v[190:193], v[26:29]
	v_mfma_f32_16x16x32_bf16 v[14:17], v[142:145], v[198:201], v[14:17]
	v_mfma_f32_16x16x32_bf16 v[10:13], v[150:153], v[198:201], v[10:13]
	s_setprio 0
	s_setprio 1
	v_mfma_f32_16x16x32_bf16 v[54:57], v[154:157], v[170:173], v[54:57]
	v_mfma_f32_16x16x32_bf16 v[50:53], v[162:165], v[170:173], v[50:53]
	v_mfma_f32_16x16x32_bf16 v[38:41], v[154:157], v[178:181], v[38:41]
	v_mfma_f32_16x16x32_bf16 v[34:37], v[162:165], v[178:181], v[34:37]
	v_mfma_f32_16x16x32_bf16 v[22:25], v[154:157], v[186:189], v[22:25]
	v_mfma_f32_16x16x32_bf16 v[18:21], v[162:165], v[186:189], v[18:21]
	v_mfma_f32_16x16x32_bf16 v[6:9], v[154:157], v[194:197], v[6:9]
	v_mfma_f32_16x16x32_bf16 v[2:5], v[162:165], v[194:197], v[2:5]
	v_mfma_f32_16x16x32_bf16 v[54:57], v[158:161], v[174:177], v[54:57]
	v_mfma_f32_16x16x32_bf16 v[50:53], v[166:169], v[174:177], v[50:53]
	v_mfma_f32_16x16x32_bf16 v[38:41], v[158:161], v[182:185], v[38:41]
	v_mfma_f32_16x16x32_bf16 v[34:37], v[166:169], v[182:185], v[34:37]
	v_mfma_f32_16x16x32_bf16 v[22:25], v[158:161], v[190:193], v[22:25]
	v_mfma_f32_16x16x32_bf16 v[18:21], v[166:169], v[190:193], v[18:21]
	v_mfma_f32_16x16x32_bf16 v[6:9], v[158:161], v[198:201], v[6:9]
	v_mfma_f32_16x16x32_bf16 v[2:5], v[166:169], v[198:201], v[2:5]
	s_setprio 0
	s_barrier
	s_add_i32 s22, 0, 0x18000
	v_add_u32_e32 v137, s22, v1
	s_add_i32 s41, 0, 0x1c000
	ds_read_b128 v[138:141], v137
	ds_read_b128 v[142:145], v137 offset:1024
	ds_read_b128 v[146:149], v137 offset:2048
	ds_read_b128 v[150:153], v137 offset:3072
	v_add_u32_e32 v137, s41, v1
	ds_read_b128 v[154:157], v137
	ds_read_b128 v[158:161], v137 offset:1024
	ds_read_b128 v[162:165], v137 offset:2048
	ds_read_b128 v[166:169], v137 offset:3072
	s_add_u32 s14, s14, s60
	s_addc_u32 s15, s15, 0
	s_mov_b32 m0, s7
	v_lshl_add_u64 v[214:215], s[14:15], 0, v[132:133]
	ds_read_b128 v[170:173], v136 offset:32768
	ds_read_b128 v[174:177], v136 offset:33792
	ds_read_b128 v[178:181], v136 offset:34816
	ds_read_b128 v[182:185], v136 offset:35840
	ds_read_b128 v[186:189], v136 offset:36864
	ds_read_b128 v[190:193], v136 offset:37888
	ds_read_b128 v[194:197], v136 offset:38912
	ds_read_b128 v[198:201], v136 offset:39936
	global_load_lds_dwordx4 v[214:215], off
	v_lshl_add_u64 v[214:215], v[214:215], 0, s[36:37]
	s_mov_b32 m0, s13
	s_nop 0
	global_load_lds_dwordx4 v[214:215], off
	s_waitcnt vmcnt(8)
	s_waitcnt lgkmcnt(0)
	s_barrier
	s_setprio 1
	s_waitcnt lgkmcnt(0)
	v_mfma_f32_16x16x32_bf16 v[126:129], v[138:141], v[170:173], v[126:129]
	v_mfma_f32_16x16x32_bf16 v[122:125], v[146:149], v[170:173], v[122:125]
	v_mfma_f32_16x16x32_bf16 v[110:113], v[138:141], v[178:181], v[110:113]
	v_mfma_f32_16x16x32_bf16 v[106:109], v[146:149], v[178:181], v[106:109]
	v_mfma_f32_16x16x32_bf16 v[94:97], v[138:141], v[186:189], v[94:97]
	v_mfma_f32_16x16x32_bf16 v[90:93], v[146:149], v[186:189], v[90:93]
	v_mfma_f32_16x16x32_bf16 v[78:81], v[138:141], v[194:197], v[78:81]
	v_mfma_f32_16x16x32_bf16 v[74:77], v[146:149], v[194:197], v[74:77]
	v_mfma_f32_16x16x32_bf16 v[126:129], v[142:145], v[174:177], v[126:129]
	v_mfma_f32_16x16x32_bf16 v[122:125], v[150:153], v[174:177], v[122:125]
	v_mfma_f32_16x16x32_bf16 v[110:113], v[142:145], v[182:185], v[110:113]
	v_mfma_f32_16x16x32_bf16 v[106:109], v[150:153], v[182:185], v[106:109]
	v_mfma_f32_16x16x32_bf16 v[94:97], v[142:145], v[190:193], v[94:97]
	v_mfma_f32_16x16x32_bf16 v[90:93], v[150:153], v[190:193], v[90:93]
	v_mfma_f32_16x16x32_bf16 v[78:81], v[142:145], v[198:201], v[78:81]
	v_mfma_f32_16x16x32_bf16 v[74:77], v[150:153], v[198:201], v[74:77]
	s_setprio 0
	s_setprio 1
	v_mfma_f32_16x16x32_bf16 v[118:121], v[154:157], v[170:173], v[118:121]
	v_mfma_f32_16x16x32_bf16 v[114:117], v[162:165], v[170:173], v[114:117]
	v_mfma_f32_16x16x32_bf16 v[102:105], v[154:157], v[178:181], v[102:105]
	v_mfma_f32_16x16x32_bf16 v[98:101], v[162:165], v[178:181], v[98:101]
	v_mfma_f32_16x16x32_bf16 v[86:89], v[154:157], v[186:189], v[86:89]
	v_mfma_f32_16x16x32_bf16 v[82:85], v[162:165], v[186:189], v[82:85]
	v_mfma_f32_16x16x32_bf16 v[70:73], v[154:157], v[194:197], v[70:73]
	v_mfma_f32_16x16x32_bf16 v[66:69], v[162:165], v[194:197], v[66:69]
	v_mfma_f32_16x16x32_bf16 v[118:121], v[158:161], v[174:177], v[118:121]
	v_mfma_f32_16x16x32_bf16 v[114:117], v[166:169], v[174:177], v[114:117]
	v_mfma_f32_16x16x32_bf16 v[102:105], v[158:161], v[182:185], v[102:105]
	v_mfma_f32_16x16x32_bf16 v[98:101], v[166:169], v[182:185], v[98:101]
	v_mfma_f32_16x16x32_bf16 v[86:89], v[158:161], v[190:193], v[86:89]
	v_mfma_f32_16x16x32_bf16 v[82:85], v[166:169], v[190:193], v[82:85]
	v_mfma_f32_16x16x32_bf16 v[70:73], v[158:161], v[198:201], v[70:73]
	v_mfma_f32_16x16x32_bf16 v[66:69], v[166:169], v[198:201], v[66:69]
	s_setprio 0
	s_barrier
; #define PG8_STAGE(bufoff, gbase, voff) do { _Pragma("unroll") for (int _i = 0; _i < 2; ++_i) \
;         __builtin_amdgcn_global_load_lds((const unsigned*)((const char*)(gbase) + (size_t)_i * r64##voff + voff), (PG8_LAS unsigned*)(lds + (bufoff) + ldsw + _i * 8192), 16, 0, 0); } while (0)
; #define PG8_LDA(dst, b, h) do { _Pragma("unroll") for (int m = 0; m < 4; ++m) _Pragma("unroll") for (int k = 0; k < 2; ++k) dst[m][k] = *(const PG8_LAS bf16x8*)(lds + PG8_SA(b, h) + aoff + m * 2048 + k * 1024); } while (0)
; #define PG8_MMA(ai, bj, At, Bt) do { __builtin_amdgcn_s_setprio(1); _Pragma("unroll") for (int m = 0; m < 4; ++m) _Pragma("unroll") for (int n = 0; n < 2; ++n) _Pragma("unroll") for (int k = 0; k < 2; ++k) \
;         acc[ai][bj][m][n] = __builtin_amdgcn_mfma_f32_16x16x32_bf16(Bt[n][k], At[m][k], acc[ai][bj][m][n], 0, 0, 0); __builtin_amdgcn_s_setprio(0); } while (0)
; #define PG8_WAIT_V(n) asm volatile("s_waitcnt vmcnt(" #n ")" ::: "memory")
; #define PG8_WAIT_L(n) asm volatile("s_waitcnt lgkmcnt(" #n ")" ::: "memory")
; #define PG8_BAR __builtin_amdgcn_s_barrier()
; #define PG8_SCHED __builtin_amdgcn_sched_barrier(0)
; template <class Epi, class Sched, bool ALIGN_EPI = false, bool SP2 = false>
; __device__ __forceinline__ void gemm_phase(PG8_LAS unsigned char* lds, const Gemm g, const Sched& S, const Epi& E, int wid0) {
;     ...
;             PG8_LDA(At, 1, 1); PG8_STAGE(PG8_SB(1, 0), b3, voffB); PG8_STAGE(PG8_SB(1, 1), b3 + hstepB, voffB); PG8_STAGE(PG8_SA(1, 0), a3, voffA);
;             PG8_WAIT_V(8); PG8_WAIT_L(0); PG8_BAR; PG8_MMA(1, 0, At, B0); PG8_MMA(1, 1, At, B1); PG8_BAR; PG8_SCHED;
;     ...
;         if constexpr (ALIGN_EPI) { if (wr == 0) PG8_BAR; }
	s_add_i32 s14, s22, s20
	v_lshl_add_u64 v[202:203], v[202:203], 0, s[70:71]
	s_mov_b32 m0, s14
	ds_read_b128 v[170:173], v136 offset:49152
	ds_read_b128 v[174:177], v136 offset:50176
	ds_read_b128 v[178:181], v136 offset:51200
	ds_read_b128 v[182:185], v136 offset:52224
	ds_read_b128 v[186:189], v136 offset:53248
	ds_read_b128 v[190:193], v136 offset:54272
	ds_read_b128 v[194:197], v136 offset:55296
	ds_read_b128 v[198:201], v136 offset:56320
	global_load_lds_dwordx4 v[202:203], off
	v_lshl_add_u64 v[202:203], v[204:205], 0, s[70:71]
	s_add_i32 m0, s14, 0x2000
	s_add_i32 s14, s41, s20
	global_load_lds_dwordx4 v[202:203], off
	v_lshl_add_u64 v[202:203], v[206:207], 0, s[70:71]
	s_mov_b32 m0, s14
	s_nop 0
	global_load_lds_dwordx4 v[202:203], off
	v_lshl_add_u64 v[202:203], v[208:209], 0, s[70:71]
	s_add_i32 m0, s14, 0x2000
	s_nop 0
	global_load_lds_dwordx4 v[202:203], off
	v_lshl_add_u64 v[202:203], v[210:211], 0, s[70:71]
	s_mov_b32 m0, s21
	s_nop 0
	global_load_lds_dwordx4 v[202:203], off
	v_lshl_add_u64 v[202:203], v[212:213], 0, s[70:71]
	s_mov_b32 m0, s23
	s_nop 0
	global_load_lds_dwordx4 v[202:203], off
	s_waitcnt vmcnt(8)
	s_waitcnt lgkmcnt(0)
	s_barrier
	s_setprio 1
	s_waitcnt lgkmcnt(0)
	v_mfma_f32_16x16x32_bf16 v[62:65], v[138:141], v[170:173], v[62:65]
	v_mfma_f32_16x16x32_bf16 v[58:61], v[146:149], v[170:173], v[58:61]
	v_mfma_f32_16x16x32_bf16 v[46:49], v[138:141], v[178:181], v[46:49]
	v_mfma_f32_16x16x32_bf16 v[42:45], v[146:149], v[178:181], v[42:45]
	v_mfma_f32_16x16x32_bf16 v[30:33], v[138:141], v[186:189], v[30:33]
	v_mfma_f32_16x16x32_bf16 v[26:29], v[146:149], v[186:189], v[26:29]
	v_mfma_f32_16x16x32_bf16 v[14:17], v[138:141], v[194:197], v[14:17]
	v_mfma_f32_16x16x32_bf16 v[10:13], v[146:149], v[194:197], v[10:13]
	v_mfma_f32_16x16x32_bf16 v[62:65], v[142:145], v[174:177], v[62:65]
	v_mfma_f32_16x16x32_bf16 v[58:61], v[150:153], v[174:177], v[58:61]
	v_mfma_f32_16x16x32_bf16 v[46:49], v[142:145], v[182:185], v[46:49]
	v_mfma_f32_16x16x32_bf16 v[42:45], v[150:153], v[182:185], v[42:45]
	v_mfma_f32_16x16x32_bf16 v[30:33], v[142:145], v[190:193], v[30:33]
	v_mfma_f32_16x16x32_bf16 v[26:29], v[150:153], v[190:193], v[26:29]
	v_mfma_f32_16x16x32_bf16 v[14:17], v[142:145], v[198:201], v[14:17]
	v_mfma_f32_16x16x32_bf16 v[10:13], v[150:153], v[198:201], v[10:13]
	s_setprio 0
	s_setprio 1
	v_mfma_f32_16x16x32_bf16 v[54:57], v[154:157], v[170:173], v[54:57]
	v_mfma_f32_16x16x32_bf16 v[50:53], v[162:165], v[170:173], v[50:53]
	v_mfma_f32_16x16x32_bf16 v[38:41], v[154:157], v[178:181], v[38:41]
	v_mfma_f32_16x16x32_bf16 v[34:37], v[162:165], v[178:181], v[34:37]
	v_mfma_f32_16x16x32_bf16 v[22:25], v[154:157], v[186:189], v[22:25]
	v_mfma_f32_16x16x32_bf16 v[18:21], v[162:165], v[186:189], v[18:21]
	v_mfma_f32_16x16x32_bf16 v[6:9], v[154:157], v[194:197], v[6:9]
	v_mfma_f32_16x16x32_bf16 v[2:5], v[162:165], v[194:197], v[2:5]
	v_mfma_f32_16x16x32_bf16 v[54:57], v[158:161], v[174:177], v[54:57]
	v_mfma_f32_16x16x32_bf16 v[50:53], v[166:169], v[174:177], v[50:53]
	v_mfma_f32_16x16x32_bf16 v[38:41], v[158:161], v[182:185], v[38:41]
	v_mfma_f32_16x16x32_bf16 v[34:37], v[166:169], v[182:185], v[34:37]
	v_mfma_f32_16x16x32_bf16 v[22:25], v[158:161], v[190:193], v[22:25]
	v_mfma_f32_16x16x32_bf16 v[18:21], v[166:169], v[190:193], v[18:21]
	v_mfma_f32_16x16x32_bf16 v[6:9], v[158:161], v[198:201], v[6:9]
	v_mfma_f32_16x16x32_bf16 v[2:5], v[166:169], v[198:201], v[2:5]
	s_setprio 0
	s_cmp_ge_u32 s44, s16
	s_mov_b32 s14, s44
	s_barrier
	s_cbranch_scc0 .LBB0_829
	s_cmpk_lt_u32 s19, 0x100
	s_cbranch_scc0 .LBB0_832
	s_barrier
